# in-proj rope epilogue: cos/sin table via 1 coalesced global load per group + per-wave LDS redistribution (was 4 strided exec-masked loads); both swizzle batches issued up front
# speedup vs baseline: 1.0096x; 1.0096x over previous
;     __device__ __forceinline__ void operator()(const f32x4 (&acc)[2][2][4][2], const Unit& u, int wr, int wc, int fr, int fq, PG8_LAS float* stash, int par, PG8_LAS unsigned char* stg, const Unit& un) const {
;     ...
;                     for (int i = 0; i < 4; ++i) { v[i] = acc[ai][bj][m][0][i] * rs; v[4 + i] = acc[ai][bj][m][1][i] * rs; }
;                     if (kind <= 1 && bj == 0) {
;                         const f32x4 c0 = *(const f32x4*)(cs + pos * 16), c1 = *(const f32x4*)(cs + pos * 16 + 4), s0 = *(const f32x4*)(cs + pos * 16 + 8), s1 = *(const f32x4*)(cs + pos * 16 + 12);
; #pragma unroll
;                         for (int i = 0; i < 8; ++i) {
;                             const float c = i < 4 ? c0[i & 3] : c1[i & 3], s = i < 4 ? s0[i & 3] : s1[i & 3];
;                             const float pr = peer_x16(v[i], fq);
;                             const float r = (fq == 0) ? (v[i] * c - pr * s) : (v[i] * c + pr * s);
;                             v[i] = (fq < 2) ? r : v[i];
;                         }
;                     }
;                     if (kind == 0) {
; #pragma unroll
;                         for (int i = 0; i < 8; ++i) v[i] *= C2Q;
;                     }
;                     { u32x4 w; w.x = cvt_pk_bf16(v[0], v[1]); w.y = cvt_pk_bf16(v[2], v[3]); w.z = cvt_pk_bf16(v[4], v[5]); w.w = cvt_pk_bf16(v[6], v[7]);
;                       *(PG8_LAS u32x4*)(stg + fr * 144 + fq * 16 + bj * 64) = w; }
;                 }
;                 {
;                     int kind;
;                     if (odd) kind = (u.pn < 6) ? 0 : (u.pn == 6 ? 1 : 2);
;                     else     kind = (u.pn < 2) ? 0 : (u.pn == 2 ? (wc < 2 ? 1 : 2) : 3);
; #pragma unroll
;                     for (int i = 0; i < 2; ++i) { const int c = fq * 16 + fr + 64 * i, rr = c >> 3, pc = c & 7;
;                         const u32x4 w = *(const PG8_LAS u32x4*)(stg + rr * 144 + pc * 16);
;                         const int rowc = row - fr + rr, posc = rowc & 4095;
;                         if (kind == 1 || kind == 2) {
;                             bf16_t* dst = (kind == 1) ? kd : vt;
;                             if (odd) *(u32x4*)(dst + (size_t)(b * 4 + wc) * (4096 * 64) + (size_t)((posc & 15) * 256 + (posc >> 4)) * 64 + pc * 8) = w;
;                             else     *(u32x4*)(dst + (size_t)(b * 2 + (wc & 1)) * (4096 * 64) + (size_t)posc * 64 + pc * 8) = w;
.Lipe_Q:
	v_mbcnt_lo_u32_b32 v166, -1, 0
	v_mbcnt_hi_u32_b32 v166, -1, v166
	v_readfirstlane_b32 s65, v180
	v_lshrrev_b32_e32 v167, 2, v166
	v_mul_u32_u24_e32 v167, 0x50, v167
	v_and_b32_e32 v168, 3, v166
	v_lshl_add_u32 v167, v168, 4, v167
	v_add_u32_e32 v167, s65, v167
	v_mul_u32_u24_e32 v168, 0x50, v141
	v_add_u32_e32 v168, s65, v168
	v_lshlrev_b32_e32 v166, 4, v166
	s_add_i32 s44, s19, 0
	s_and_b32 s44, s44, 0xfff
	s_lshl_b32 s44, s44, 6
	s_add_u32 s44, s62, s44
	s_addc_u32 s45, s63, 0
	global_load_dwordx4 v[154:157], v166, s[44:45]
	s_add_i32 s44, s19, 16
	s_and_b32 s44, s44, 0xfff
	s_lshl_b32 s44, s44, 6
	s_add_u32 s44, s62, s44
	s_addc_u32 s45, s63, 0
	global_load_dwordx4 v[158:161], v166, s[44:45]
	s_waitcnt vmcnt(1)
	ds_write_b128 v167, v[154:157]
	ds_read_b128 v[218:221], v168
	ds_read_b128 v[222:225], v168 offset:16
	ds_read_b128 v[226:229], v168 offset:32
	ds_read_b128 v[230:233], v168 offset:48
	v_pk_mul_f32 v[118:119], v[118:119], v[152:153] op_sel_hi:[1,0]
	v_pk_mul_f32 v[120:121], v[120:121], v[152:153] op_sel_hi:[1,0]
	v_pk_mul_f32 v[114:115], v[114:115], v[152:153] op_sel_hi:[1,0]
	v_pk_mul_f32 v[116:117], v[116:117], v[152:153] op_sel_hi:[1,0]
	v_pk_mul_f32 v[118:119], v[118:119], s[30:31] op_sel_hi:[1,0]
	v_pk_mul_f32 v[120:121], v[120:121], s[30:31] op_sel_hi:[1,0]
	v_pk_mul_f32 v[114:115], v[114:115], s[30:31] op_sel_hi:[1,0]
	v_pk_mul_f32 v[116:117], v[116:117], s[30:31] op_sel_hi:[1,0]
	v_cvt_pk_bf16_f32 v118, v118, v119
	v_cvt_pk_bf16_f32 v119, v120, v121
	v_cvt_pk_bf16_f32 v120, v114, v115
	v_cvt_pk_bf16_f32 v121, v116, v117
	v_pk_mul_f32 v[126:127], v[126:127], v[152:153] op_sel_hi:[1,0]
	v_pk_mul_f32 v[128:129], v[128:129], v[152:153] op_sel_hi:[1,0]
	v_pk_mul_f32 v[122:123], v[122:123], v[152:153] op_sel_hi:[1,0]
	v_pk_mul_f32 v[124:125], v[124:125], v[152:153] op_sel_hi:[1,0]
	ds_swizzle_b32 v114, v126 offset:0x401f
	ds_swizzle_b32 v115, v127 offset:0x401f
	ds_swizzle_b32 v116, v128 offset:0x401f
	ds_swizzle_b32 v117, v129 offset:0x401f
	ds_swizzle_b32 v162, v122 offset:0x401f
	ds_swizzle_b32 v163, v123 offset:0x401f
	ds_swizzle_b32 v164, v124 offset:0x401f
	ds_swizzle_b32 v165, v125 offset:0x401f
	s_waitcnt lgkmcnt(8)
	v_xor_b32_e32 v226, v201, v226
	v_xor_b32_e32 v227, v201, v227
	v_xor_b32_e32 v228, v201, v228
	v_xor_b32_e32 v229, v201, v229
	v_xor_b32_e32 v230, v201, v230
	v_xor_b32_e32 v231, v201, v231
	v_xor_b32_e32 v232, v201, v232
	v_xor_b32_e32 v233, v201, v233
	s_waitcnt lgkmcnt(4)
	v_mul_f32_e32 v114, v226, v114
	v_fmac_f32_e32 v114, v126, v218
	v_cndmask_b32_e64 v126, v126, v114, s[38:39]
	v_mul_f32_e32 v115, v227, v115
	v_fmac_f32_e32 v115, v127, v219
	v_cndmask_b32_e64 v127, v127, v115, s[38:39]
	v_mul_f32_e32 v116, v228, v116
	v_fmac_f32_e32 v116, v128, v220
	v_cndmask_b32_e64 v128, v128, v116, s[38:39]
	v_mul_f32_e32 v117, v229, v117
	v_fmac_f32_e32 v117, v129, v221
	v_cndmask_b32_e64 v129, v129, v117, s[38:39]
	s_waitcnt lgkmcnt(0)
	v_mul_f32_e32 v162, v230, v162
	v_fmac_f32_e32 v162, v122, v222
	v_cndmask_b32_e64 v122, v122, v162, s[38:39]
	v_mul_f32_e32 v163, v231, v163
	v_fmac_f32_e32 v163, v123, v223
	v_cndmask_b32_e64 v123, v123, v163, s[38:39]
	v_mul_f32_e32 v164, v232, v164
	v_fmac_f32_e32 v164, v124, v224
	v_cndmask_b32_e64 v124, v124, v164, s[38:39]
	v_mul_f32_e32 v165, v233, v165
	v_fmac_f32_e32 v165, v125, v225
	v_cndmask_b32_e64 v125, v125, v165, s[38:39]
	v_pk_mul_f32 v[126:127], v[126:127], s[30:31] op_sel_hi:[1,0]
	v_pk_mul_f32 v[128:129], v[128:129], s[30:31] op_sel_hi:[1,0]
	v_pk_mul_f32 v[122:123], v[122:123], s[30:31] op_sel_hi:[1,0]
	v_pk_mul_f32 v[124:125], v[124:125], s[30:31] op_sel_hi:[1,0]
	v_cvt_pk_bf16_f32 v126, v126, v127
	v_cvt_pk_bf16_f32 v127, v128, v129
	v_cvt_pk_bf16_f32 v128, v122, v123
	v_cvt_pk_bf16_f32 v129, v124, v125
	ds_write_b128 v178, v[126:129]
	ds_write_b128 v178, v[118:121] offset:64
	ds_read_b128 v[122:125], v180
	ds_read_b128 v[114:117], v180 offset:1152
	s_add_i32 s44, s19, 32
	s_and_b32 s44, s44, 0xfff
	s_lshl_b32 s44, s44, 6
	s_add_u32 s44, s62, s44
	s_addc_u32 s45, s63, 0
	global_load_dwordx4 v[154:157], v166, s[44:45]
	s_waitcnt vmcnt(1)
	ds_write_b128 v167, v[158:161]
	ds_read_b128 v[218:221], v168
	ds_read_b128 v[222:225], v168 offset:16
	ds_read_b128 v[226:229], v168 offset:32
	ds_read_b128 v[230:233], v168 offset:48
	v_pk_mul_f32 v[102:103], v[102:103], v[152:153] op_sel:[0,1]
	v_pk_mul_f32 v[104:105], v[104:105], v[152:153] op_sel:[0,1]
	v_pk_mul_f32 v[98:99], v[98:99], v[152:153] op_sel:[0,1]
	v_pk_mul_f32 v[100:101], v[100:101], v[152:153] op_sel:[0,1]
	v_pk_mul_f32 v[102:103], v[102:103], s[30:31] op_sel_hi:[1,0]
	v_pk_mul_f32 v[104:105], v[104:105], s[30:31] op_sel_hi:[1,0]
	v_pk_mul_f32 v[98:99], v[98:99], s[30:31] op_sel_hi:[1,0]
	v_pk_mul_f32 v[100:101], v[100:101], s[30:31] op_sel_hi:[1,0]
	v_cvt_pk_bf16_f32 v102, v102, v103
	v_cvt_pk_bf16_f32 v103, v104, v105
	v_cvt_pk_bf16_f32 v104, v98, v99
	v_cvt_pk_bf16_f32 v105, v100, v101
	v_pk_mul_f32 v[110:111], v[110:111], v[152:153] op_sel:[0,1]
	v_pk_mul_f32 v[112:113], v[112:113], v[152:153] op_sel:[0,1]
	v_pk_mul_f32 v[106:107], v[106:107], v[152:153] op_sel:[0,1]
	v_pk_mul_f32 v[108:109], v[108:109], v[152:153] op_sel:[0,1]
	ds_swizzle_b32 v98, v110 offset:0x401f
	ds_swizzle_b32 v99, v111 offset:0x401f
	ds_swizzle_b32 v100, v112 offset:0x401f
	ds_swizzle_b32 v101, v113 offset:0x401f
	ds_swizzle_b32 v162, v106 offset:0x401f
	ds_swizzle_b32 v163, v107 offset:0x401f
	ds_swizzle_b32 v164, v108 offset:0x401f
	ds_swizzle_b32 v165, v109 offset:0x401f
	s_waitcnt lgkmcnt(8)
;     __device__ __forceinline__ void operator()(const f32x4 (&acc)[2][2][4][2], const Unit& u, int wr, int wc, int fr, int fq, PG8_LAS float* stash, int par, PG8_LAS unsigned char* stg, const Unit& un) const {
;     ...
;                     for (int i = 0; i < 4; ++i) { v[i] = acc[ai][bj][m][0][i] * rs; v[4 + i] = acc[ai][bj][m][1][i] * rs; }
;                     if (kind <= 1 && bj == 0) {
;                         const f32x4 c0 = *(const f32x4*)(cs + pos * 16), c1 = *(const f32x4*)(cs + pos * 16 + 4), s0 = *(const f32x4*)(cs + pos * 16 + 8), s1 = *(const f32x4*)(cs + pos * 16 + 12);
; #pragma unroll
;                         for (int i = 0; i < 8; ++i) {
;                             const float c = i < 4 ? c0[i & 3] : c1[i & 3], s = i < 4 ? s0[i & 3] : s1[i & 3];
;                             const float pr = peer_x16(v[i], fq);
;                             const float r = (fq == 0) ? (v[i] * c - pr * s) : (v[i] * c + pr * s);
;                             v[i] = (fq < 2) ? r : v[i];
;                         }
;                     }
;                     if (kind == 0) {
; #pragma unroll
;                         for (int i = 0; i < 8; ++i) v[i] *= C2Q;
;                     }
;                     { u32x4 w; w.x = cvt_pk_bf16(v[0], v[1]); w.y = cvt_pk_bf16(v[2], v[3]); w.z = cvt_pk_bf16(v[4], v[5]); w.w = cvt_pk_bf16(v[6], v[7]);
;                       *(PG8_LAS u32x4*)(stg + fr * 144 + fq * 16 + bj * 64) = w; }
;                 }
;                 {
;                     int kind;
;                     if (odd) kind = (u.pn < 6) ? 0 : (u.pn == 6 ? 1 : 2);
;                     else     kind = (u.pn < 2) ? 0 : (u.pn == 2 ? (wc < 2 ? 1 : 2) : 3);
; #pragma unroll
;                     for (int i = 0; i < 2; ++i) { const int c = fq * 16 + fr + 64 * i, rr = c >> 3, pc = c & 7;
;                         const u32x4 w = *(const PG8_LAS u32x4*)(stg + rr * 144 + pc * 16);
;                         const int rowc = row - fr + rr, posc = rowc & 4095;
;                         if (kind == 1 || kind == 2) {
;                             bf16_t* dst = (kind == 1) ? kd : vt;
;                             if (odd) *(u32x4*)(dst + (size_t)(b * 4 + wc) * (4096 * 64) + (size_t)((posc & 15) * 256 + (posc >> 4)) * 64 + pc * 8) = w;
;                             else     *(u32x4*)(dst + (size_t)(b * 2 + (wc & 1)) * (4096 * 64) + (size_t)posc * 64 + pc * 8) = w;
	v_xor_b32_e32 v226, v201, v226
	v_xor_b32_e32 v227, v201, v227
	v_xor_b32_e32 v228, v201, v228
	v_xor_b32_e32 v229, v201, v229
	v_xor_b32_e32 v230, v201, v230
	v_xor_b32_e32 v231, v201, v231
	v_xor_b32_e32 v232, v201, v232
	v_xor_b32_e32 v233, v201, v233
	s_waitcnt lgkmcnt(4)
	v_mul_f32_e32 v98, v226, v98
	v_fmac_f32_e32 v98, v110, v218
	v_cndmask_b32_e64 v110, v110, v98, s[38:39]
	v_mul_f32_e32 v99, v227, v99
	v_fmac_f32_e32 v99, v111, v219
	v_cndmask_b32_e64 v111, v111, v99, s[38:39]
	v_mul_f32_e32 v100, v228, v100
	v_fmac_f32_e32 v100, v112, v220
	v_cndmask_b32_e64 v112, v112, v100, s[38:39]
	v_mul_f32_e32 v101, v229, v101
	v_fmac_f32_e32 v101, v113, v221
	v_cndmask_b32_e64 v113, v113, v101, s[38:39]
	s_waitcnt lgkmcnt(0)
	v_mul_f32_e32 v162, v230, v162
	v_fmac_f32_e32 v162, v106, v222
	v_cndmask_b32_e64 v106, v106, v162, s[38:39]
	v_mul_f32_e32 v163, v231, v163
	v_fmac_f32_e32 v163, v107, v223
	v_cndmask_b32_e64 v107, v107, v163, s[38:39]
	v_mul_f32_e32 v164, v232, v164
	v_fmac_f32_e32 v164, v108, v224
	v_cndmask_b32_e64 v108, v108, v164, s[38:39]
	v_mul_f32_e32 v165, v233, v165
	v_fmac_f32_e32 v165, v109, v225
	v_cndmask_b32_e64 v109, v109, v165, s[38:39]
	v_pk_mul_f32 v[110:111], v[110:111], s[30:31] op_sel_hi:[1,0]
	v_pk_mul_f32 v[112:113], v[112:113], s[30:31] op_sel_hi:[1,0]
	v_pk_mul_f32 v[106:107], v[106:107], s[30:31] op_sel_hi:[1,0]
	v_pk_mul_f32 v[108:109], v[108:109], s[30:31] op_sel_hi:[1,0]
	v_cvt_pk_bf16_f32 v110, v110, v111
	v_cvt_pk_bf16_f32 v111, v112, v113
	v_cvt_pk_bf16_f32 v112, v106, v107
	v_cvt_pk_bf16_f32 v113, v108, v109
	s_mov_b32 s100, s98
	s_mov_b32 s101, s99
	global_store_dwordx4 v200, v[122:125], s[100:101] nt
	s_add_u32 s100, s100, s67
	s_addc_u32 s101, s101, 0
	global_store_dwordx4 v200, v[114:117], s[100:101] nt
	ds_write_b128 v178, v[110:113]
	ds_write_b128 v178, v[102:105] offset:64
	ds_read_b128 v[106:109], v180
	ds_read_b128 v[98:101], v180 offset:1152
	s_add_i32 s44, s19, 48
	s_and_b32 s44, s44, 0xfff
	s_lshl_b32 s44, s44, 6
	s_add_u32 s44, s62, s44
	s_addc_u32 s45, s63, 0
	global_load_dwordx4 v[158:161], v166, s[44:45]
	s_waitcnt vmcnt(3)
	ds_write_b128 v167, v[154:157]
	ds_read_b128 v[218:221], v168
	ds_read_b128 v[222:225], v168 offset:16
	ds_read_b128 v[226:229], v168 offset:32
	ds_read_b128 v[230:233], v168 offset:48
	v_pk_mul_f32 v[86:87], v[86:87], v[150:151] op_sel_hi:[1,0]
	v_pk_mul_f32 v[88:89], v[88:89], v[150:151] op_sel_hi:[1,0]
	v_pk_mul_f32 v[82:83], v[82:83], v[150:151] op_sel_hi:[1,0]
	v_pk_mul_f32 v[84:85], v[84:85], v[150:151] op_sel_hi:[1,0]
	v_pk_mul_f32 v[86:87], v[86:87], s[30:31] op_sel_hi:[1,0]
	v_pk_mul_f32 v[88:89], v[88:89], s[30:31] op_sel_hi:[1,0]
	v_pk_mul_f32 v[82:83], v[82:83], s[30:31] op_sel_hi:[1,0]
	v_pk_mul_f32 v[84:85], v[84:85], s[30:31] op_sel_hi:[1,0]
	v_cvt_pk_bf16_f32 v86, v86, v87
	v_cvt_pk_bf16_f32 v87, v88, v89
	v_cvt_pk_bf16_f32 v88, v82, v83
	v_cvt_pk_bf16_f32 v89, v84, v85
	v_pk_mul_f32 v[94:95], v[94:95], v[150:151] op_sel_hi:[1,0]
	v_pk_mul_f32 v[96:97], v[96:97], v[150:151] op_sel_hi:[1,0]
	v_pk_mul_f32 v[90:91], v[90:91], v[150:151] op_sel_hi:[1,0]
	v_pk_mul_f32 v[92:93], v[92:93], v[150:151] op_sel_hi:[1,0]
	ds_swizzle_b32 v82, v94 offset:0x401f
	ds_swizzle_b32 v83, v95 offset:0x401f
	ds_swizzle_b32 v84, v96 offset:0x401f
	ds_swizzle_b32 v85, v97 offset:0x401f
	ds_swizzle_b32 v162, v90 offset:0x401f
	ds_swizzle_b32 v163, v91 offset:0x401f
	ds_swizzle_b32 v164, v92 offset:0x401f
	ds_swizzle_b32 v165, v93 offset:0x401f
	s_waitcnt lgkmcnt(8)
	v_xor_b32_e32 v226, v201, v226
	v_xor_b32_e32 v227, v201, v227
	v_xor_b32_e32 v228, v201, v228
	v_xor_b32_e32 v229, v201, v229
	v_xor_b32_e32 v230, v201, v230
	v_xor_b32_e32 v231, v201, v231
	v_xor_b32_e32 v232, v201, v232
	v_xor_b32_e32 v233, v201, v233
	s_waitcnt lgkmcnt(4)
	v_mul_f32_e32 v82, v226, v82
	v_fmac_f32_e32 v82, v94, v218
	v_cndmask_b32_e64 v94, v94, v82, s[38:39]
	v_mul_f32_e32 v83, v227, v83
	v_fmac_f32_e32 v83, v95, v219
	v_cndmask_b32_e64 v95, v95, v83, s[38:39]
	v_mul_f32_e32 v84, v228, v84
	v_fmac_f32_e32 v84, v96, v220
	v_cndmask_b32_e64 v96, v96, v84, s[38:39]
	v_mul_f32_e32 v85, v229, v85
	v_fmac_f32_e32 v85, v97, v221
	v_cndmask_b32_e64 v97, v97, v85, s[38:39]
	s_waitcnt lgkmcnt(0)
	v_mul_f32_e32 v162, v230, v162
	v_fmac_f32_e32 v162, v90, v222
	v_cndmask_b32_e64 v90, v90, v162, s[38:39]
	v_mul_f32_e32 v163, v231, v163
	v_fmac_f32_e32 v163, v91, v223
	v_cndmask_b32_e64 v91, v91, v163, s[38:39]
	v_mul_f32_e32 v164, v232, v164
	v_fmac_f32_e32 v164, v92, v224
	v_cndmask_b32_e64 v92, v92, v164, s[38:39]
	v_mul_f32_e32 v165, v233, v165
	v_fmac_f32_e32 v165, v93, v225
	v_cndmask_b32_e64 v93, v93, v165, s[38:39]
	v_pk_mul_f32 v[94:95], v[94:95], s[30:31] op_sel_hi:[1,0]
	v_pk_mul_f32 v[96:97], v[96:97], s[30:31] op_sel_hi:[1,0]
	v_pk_mul_f32 v[90:91], v[90:91], s[30:31] op_sel_hi:[1,0]
	v_pk_mul_f32 v[92:93], v[92:93], s[30:31] op_sel_hi:[1,0]
	v_cvt_pk_bf16_f32 v94, v94, v95
	v_cvt_pk_bf16_f32 v95, v96, v97
	v_cvt_pk_bf16_f32 v96, v90, v91
	v_cvt_pk_bf16_f32 v97, v92, v93
	s_mul_i32 s44, s66, 16
	s_add_u32 s100, s98, s44
	s_addc_u32 s101, s99, 0
	global_store_dwordx4 v200, v[106:109], s[100:101] nt
	s_add_u32 s100, s100, s67
	s_addc_u32 s101, s101, 0
	global_store_dwordx4 v200, v[98:101], s[100:101] nt
	ds_write_b128 v178, v[94:97]
	ds_write_b128 v178, v[86:89] offset:64
	ds_read_b128 v[90:93], v180
	ds_read_b128 v[82:85], v180 offset:1152
	s_add_i32 s44, s19, 128
	s_and_b32 s44, s44, 0xfff
	s_lshl_b32 s44, s44, 6
	s_add_u32 s44, s62, s44
	s_addc_u32 s45, s63, 0
	global_load_dwordx4 v[154:157], v166, s[44:45]
	s_waitcnt vmcnt(3)
;     __device__ __forceinline__ void operator()(const f32x4 (&acc)[2][2][4][2], const Unit& u, int wr, int wc, int fr, int fq, PG8_LAS float* stash, int par, PG8_LAS unsigned char* stg, const Unit& un) const {
;     ...
;                     for (int i = 0; i < 4; ++i) { v[i] = acc[ai][bj][m][0][i] * rs; v[4 + i] = acc[ai][bj][m][1][i] * rs; }
;                     if (kind <= 1 && bj == 0) {
;                         const f32x4 c0 = *(const f32x4*)(cs + pos * 16), c1 = *(const f32x4*)(cs + pos * 16 + 4), s0 = *(const f32x4*)(cs + pos * 16 + 8), s1 = *(const f32x4*)(cs + pos * 16 + 12);
; #pragma unroll
;                         for (int i = 0; i < 8; ++i) {
;                             const float c = i < 4 ? c0[i & 3] : c1[i & 3], s = i < 4 ? s0[i & 3] : s1[i & 3];
;                             const float pr = peer_x16(v[i], fq);
;                             const float r = (fq == 0) ? (v[i] * c - pr * s) : (v[i] * c + pr * s);
;                             v[i] = (fq < 2) ? r : v[i];
;                         }
;                     }
;                     if (kind == 0) {
; #pragma unroll
;                         for (int i = 0; i < 8; ++i) v[i] *= C2Q;
;                     }
;                     { u32x4 w; w.x = cvt_pk_bf16(v[0], v[1]); w.y = cvt_pk_bf16(v[2], v[3]); w.z = cvt_pk_bf16(v[4], v[5]); w.w = cvt_pk_bf16(v[6], v[7]);
;                       *(PG8_LAS u32x4*)(stg + fr * 144 + fq * 16 + bj * 64) = w; }
;                 }
;                 {
;                     int kind;
;                     if (odd) kind = (u.pn < 6) ? 0 : (u.pn == 6 ? 1 : 2);
;                     else     kind = (u.pn < 2) ? 0 : (u.pn == 2 ? (wc < 2 ? 1 : 2) : 3);
; #pragma unroll
;                     for (int i = 0; i < 2; ++i) { const int c = fq * 16 + fr + 64 * i, rr = c >> 3, pc = c & 7;
;                         const u32x4 w = *(const PG8_LAS u32x4*)(stg + rr * 144 + pc * 16);
;                         const int rowc = row - fr + rr, posc = rowc & 4095;
;                         if (kind == 1 || kind == 2) {
;                             bf16_t* dst = (kind == 1) ? kd : vt;
;                             if (odd) *(u32x4*)(dst + (size_t)(b * 4 + wc) * (4096 * 64) + (size_t)((posc & 15) * 256 + (posc >> 4)) * 64 + pc * 8) = w;
;                             else     *(u32x4*)(dst + (size_t)(b * 2 + (wc & 1)) * (4096 * 64) + (size_t)posc * 64 + pc * 8) = w;
	ds_write_b128 v167, v[158:161]
	ds_read_b128 v[218:221], v168
	ds_read_b128 v[222:225], v168 offset:16
	ds_read_b128 v[226:229], v168 offset:32
	ds_read_b128 v[230:233], v168 offset:48
	v_pk_mul_f32 v[70:71], v[70:71], v[150:151] op_sel:[0,1]
	v_pk_mul_f32 v[72:73], v[72:73], v[150:151] op_sel:[0,1]
	v_pk_mul_f32 v[66:67], v[66:67], v[150:151] op_sel:[0,1]
	v_pk_mul_f32 v[68:69], v[68:69], v[150:151] op_sel:[0,1]
	v_pk_mul_f32 v[70:71], v[70:71], s[30:31] op_sel_hi:[1,0]
	v_pk_mul_f32 v[72:73], v[72:73], s[30:31] op_sel_hi:[1,0]
	v_pk_mul_f32 v[66:67], v[66:67], s[30:31] op_sel_hi:[1,0]
	v_pk_mul_f32 v[68:69], v[68:69], s[30:31] op_sel_hi:[1,0]
	v_cvt_pk_bf16_f32 v70, v70, v71
	v_cvt_pk_bf16_f32 v71, v72, v73
	v_cvt_pk_bf16_f32 v72, v66, v67
	v_cvt_pk_bf16_f32 v73, v68, v69
	v_pk_mul_f32 v[78:79], v[78:79], v[150:151] op_sel:[0,1]
	v_pk_mul_f32 v[80:81], v[80:81], v[150:151] op_sel:[0,1]
	v_pk_mul_f32 v[74:75], v[74:75], v[150:151] op_sel:[0,1]
	v_pk_mul_f32 v[76:77], v[76:77], v[150:151] op_sel:[0,1]
	ds_swizzle_b32 v66, v78 offset:0x401f
	ds_swizzle_b32 v67, v79 offset:0x401f
	ds_swizzle_b32 v68, v80 offset:0x401f
	ds_swizzle_b32 v69, v81 offset:0x401f
	ds_swizzle_b32 v162, v74 offset:0x401f
	ds_swizzle_b32 v163, v75 offset:0x401f
	ds_swizzle_b32 v164, v76 offset:0x401f
	ds_swizzle_b32 v165, v77 offset:0x401f
	s_waitcnt lgkmcnt(8)
	v_xor_b32_e32 v226, v201, v226
	v_xor_b32_e32 v227, v201, v227
	v_xor_b32_e32 v228, v201, v228
	v_xor_b32_e32 v229, v201, v229
	v_xor_b32_e32 v230, v201, v230
	v_xor_b32_e32 v231, v201, v231
	v_xor_b32_e32 v232, v201, v232
	v_xor_b32_e32 v233, v201, v233
	s_waitcnt lgkmcnt(4)
	v_mul_f32_e32 v66, v226, v66
	v_fmac_f32_e32 v66, v78, v218
	v_cndmask_b32_e64 v78, v78, v66, s[38:39]
	v_mul_f32_e32 v67, v227, v67
	v_fmac_f32_e32 v67, v79, v219
	v_cndmask_b32_e64 v79, v79, v67, s[38:39]
	v_mul_f32_e32 v68, v228, v68
	v_fmac_f32_e32 v68, v80, v220
	v_cndmask_b32_e64 v80, v80, v68, s[38:39]
	v_mul_f32_e32 v69, v229, v69
	v_fmac_f32_e32 v69, v81, v221
	v_cndmask_b32_e64 v81, v81, v69, s[38:39]
	s_waitcnt lgkmcnt(0)
	v_mul_f32_e32 v162, v230, v162
	v_fmac_f32_e32 v162, v74, v222
	v_cndmask_b32_e64 v74, v74, v162, s[38:39]
	v_mul_f32_e32 v163, v231, v163
	v_fmac_f32_e32 v163, v75, v223
	v_cndmask_b32_e64 v75, v75, v163, s[38:39]
	v_mul_f32_e32 v164, v232, v164
	v_fmac_f32_e32 v164, v76, v224
	v_cndmask_b32_e64 v76, v76, v164, s[38:39]
	v_mul_f32_e32 v165, v233, v165
	v_fmac_f32_e32 v165, v77, v225
	v_cndmask_b32_e64 v77, v77, v165, s[38:39]
	v_pk_mul_f32 v[78:79], v[78:79], s[30:31] op_sel_hi:[1,0]
	v_pk_mul_f32 v[80:81], v[80:81], s[30:31] op_sel_hi:[1,0]
	v_pk_mul_f32 v[74:75], v[74:75], s[30:31] op_sel_hi:[1,0]
	v_pk_mul_f32 v[76:77], v[76:77], s[30:31] op_sel_hi:[1,0]
	v_cvt_pk_bf16_f32 v78, v78, v79
	v_cvt_pk_bf16_f32 v79, v80, v81
	v_cvt_pk_bf16_f32 v80, v74, v75
	v_cvt_pk_bf16_f32 v81, v76, v77
	s_mul_i32 s44, s66, 32
	s_add_u32 s100, s98, s44
	s_addc_u32 s101, s99, 0
	global_store_dwordx4 v200, v[90:93], s[100:101] nt
	s_add_u32 s100, s100, s67
	s_addc_u32 s101, s101, 0
	global_store_dwordx4 v200, v[82:85], s[100:101] nt
	ds_write_b128 v178, v[78:81]
	ds_write_b128 v178, v[70:73] offset:64
	ds_read_b128 v[74:77], v180
	ds_read_b128 v[66:69], v180 offset:1152
	s_add_i32 s44, s19, 144
	s_and_b32 s44, s44, 0xfff
	s_lshl_b32 s44, s44, 6
	s_add_u32 s44, s62, s44
	s_addc_u32 s45, s63, 0
	global_load_dwordx4 v[158:161], v166, s[44:45]
	s_waitcnt vmcnt(3)
	ds_write_b128 v167, v[154:157]
	ds_read_b128 v[218:221], v168
	ds_read_b128 v[222:225], v168 offset:16
	ds_read_b128 v[226:229], v168 offset:32
	ds_read_b128 v[230:233], v168 offset:48
	v_pk_mul_f32 v[54:55], v[54:55], v[148:149] op_sel_hi:[1,0]
	v_pk_mul_f32 v[56:57], v[56:57], v[148:149] op_sel_hi:[1,0]
	v_pk_mul_f32 v[50:51], v[50:51], v[148:149] op_sel_hi:[1,0]
	v_pk_mul_f32 v[52:53], v[52:53], v[148:149] op_sel_hi:[1,0]
	v_pk_mul_f32 v[54:55], v[54:55], s[30:31] op_sel_hi:[1,0]
	v_pk_mul_f32 v[56:57], v[56:57], s[30:31] op_sel_hi:[1,0]
	v_pk_mul_f32 v[50:51], v[50:51], s[30:31] op_sel_hi:[1,0]
	v_pk_mul_f32 v[52:53], v[52:53], s[30:31] op_sel_hi:[1,0]
	v_cvt_pk_bf16_f32 v54, v54, v55
	v_cvt_pk_bf16_f32 v55, v56, v57
	v_cvt_pk_bf16_f32 v56, v50, v51
	v_cvt_pk_bf16_f32 v57, v52, v53
	v_pk_mul_f32 v[62:63], v[62:63], v[148:149] op_sel_hi:[1,0]
	v_pk_mul_f32 v[64:65], v[64:65], v[148:149] op_sel_hi:[1,0]
	v_pk_mul_f32 v[58:59], v[58:59], v[148:149] op_sel_hi:[1,0]
	v_pk_mul_f32 v[60:61], v[60:61], v[148:149] op_sel_hi:[1,0]
	ds_swizzle_b32 v50, v62 offset:0x401f
	ds_swizzle_b32 v51, v63 offset:0x401f
	ds_swizzle_b32 v52, v64 offset:0x401f
	ds_swizzle_b32 v53, v65 offset:0x401f
	ds_swizzle_b32 v162, v58 offset:0x401f
	ds_swizzle_b32 v163, v59 offset:0x401f
	ds_swizzle_b32 v164, v60 offset:0x401f
	ds_swizzle_b32 v165, v61 offset:0x401f
	s_waitcnt lgkmcnt(8)
	v_xor_b32_e32 v226, v201, v226
	v_xor_b32_e32 v227, v201, v227
	v_xor_b32_e32 v228, v201, v228
	v_xor_b32_e32 v229, v201, v229
	v_xor_b32_e32 v230, v201, v230
	v_xor_b32_e32 v231, v201, v231
	v_xor_b32_e32 v232, v201, v232
	v_xor_b32_e32 v233, v201, v233
	s_waitcnt lgkmcnt(4)
	v_mul_f32_e32 v50, v226, v50
	v_fmac_f32_e32 v50, v62, v218
	v_cndmask_b32_e64 v62, v62, v50, s[38:39]
	v_mul_f32_e32 v51, v227, v51
	v_fmac_f32_e32 v51, v63, v219
	v_cndmask_b32_e64 v63, v63, v51, s[38:39]
	v_mul_f32_e32 v52, v228, v52
	v_fmac_f32_e32 v52, v64, v220
	v_cndmask_b32_e64 v64, v64, v52, s[38:39]
	v_mul_f32_e32 v53, v229, v53
	v_fmac_f32_e32 v53, v65, v221
	v_cndmask_b32_e64 v65, v65, v53, s[38:39]
	s_waitcnt lgkmcnt(0)
;     __device__ __forceinline__ void operator()(const f32x4 (&acc)[2][2][4][2], const Unit& u, int wr, int wc, int fr, int fq, PG8_LAS float* stash, int par, PG8_LAS unsigned char* stg, const Unit& un) const {
;     ...
;                     for (int i = 0; i < 4; ++i) { v[i] = acc[ai][bj][m][0][i] * rs; v[4 + i] = acc[ai][bj][m][1][i] * rs; }
;                     if (kind <= 1 && bj == 0) {
;                         const f32x4 c0 = *(const f32x4*)(cs + pos * 16), c1 = *(const f32x4*)(cs + pos * 16 + 4), s0 = *(const f32x4*)(cs + pos * 16 + 8), s1 = *(const f32x4*)(cs + pos * 16 + 12);
; #pragma unroll
;                         for (int i = 0; i < 8; ++i) {
;                             const float c = i < 4 ? c0[i & 3] : c1[i & 3], s = i < 4 ? s0[i & 3] : s1[i & 3];
;                             const float pr = peer_x16(v[i], fq);
;                             const float r = (fq == 0) ? (v[i] * c - pr * s) : (v[i] * c + pr * s);
;                             v[i] = (fq < 2) ? r : v[i];
;                         }
;                     }
;                     if (kind == 0) {
; #pragma unroll
;                         for (int i = 0; i < 8; ++i) v[i] *= C2Q;
;                     }
;                     { u32x4 w; w.x = cvt_pk_bf16(v[0], v[1]); w.y = cvt_pk_bf16(v[2], v[3]); w.z = cvt_pk_bf16(v[4], v[5]); w.w = cvt_pk_bf16(v[6], v[7]);
;                       *(PG8_LAS u32x4*)(stg + fr * 144 + fq * 16 + bj * 64) = w; }
;                 }
;                 {
;                     int kind;
;                     if (odd) kind = (u.pn < 6) ? 0 : (u.pn == 6 ? 1 : 2);
;                     else     kind = (u.pn < 2) ? 0 : (u.pn == 2 ? (wc < 2 ? 1 : 2) : 3);
; #pragma unroll
;                     for (int i = 0; i < 2; ++i) { const int c = fq * 16 + fr + 64 * i, rr = c >> 3, pc = c & 7;
;                         const u32x4 w = *(const PG8_LAS u32x4*)(stg + rr * 144 + pc * 16);
;                         const int rowc = row - fr + rr, posc = rowc & 4095;
;                         if (kind == 1 || kind == 2) {
;                             bf16_t* dst = (kind == 1) ? kd : vt;
;                             if (odd) *(u32x4*)(dst + (size_t)(b * 4 + wc) * (4096 * 64) + (size_t)((posc & 15) * 256 + (posc >> 4)) * 64 + pc * 8) = w;
;                             else     *(u32x4*)(dst + (size_t)(b * 2 + (wc & 1)) * (4096 * 64) + (size_t)posc * 64 + pc * 8) = w;
	v_mul_f32_e32 v162, v230, v162
	v_fmac_f32_e32 v162, v58, v222
	v_cndmask_b32_e64 v58, v58, v162, s[38:39]
	v_mul_f32_e32 v163, v231, v163
	v_fmac_f32_e32 v163, v59, v223
	v_cndmask_b32_e64 v59, v59, v163, s[38:39]
	v_mul_f32_e32 v164, v232, v164
	v_fmac_f32_e32 v164, v60, v224
	v_cndmask_b32_e64 v60, v60, v164, s[38:39]
	v_mul_f32_e32 v165, v233, v165
	v_fmac_f32_e32 v165, v61, v225
	v_cndmask_b32_e64 v61, v61, v165, s[38:39]
	v_pk_mul_f32 v[62:63], v[62:63], s[30:31] op_sel_hi:[1,0]
	v_pk_mul_f32 v[64:65], v[64:65], s[30:31] op_sel_hi:[1,0]
	v_pk_mul_f32 v[58:59], v[58:59], s[30:31] op_sel_hi:[1,0]
	v_pk_mul_f32 v[60:61], v[60:61], s[30:31] op_sel_hi:[1,0]
	v_cvt_pk_bf16_f32 v62, v62, v63
	v_cvt_pk_bf16_f32 v63, v64, v65
	v_cvt_pk_bf16_f32 v64, v58, v59
	v_cvt_pk_bf16_f32 v65, v60, v61
	s_mul_i32 s44, s66, 48
	s_add_u32 s100, s98, s44
	s_addc_u32 s101, s99, 0
	global_store_dwordx4 v200, v[74:77], s[100:101] nt
	s_add_u32 s100, s100, s67
	s_addc_u32 s101, s101, 0
	global_store_dwordx4 v200, v[66:69], s[100:101] nt
	ds_write_b128 v178, v[62:65]
	ds_write_b128 v178, v[54:57] offset:64
	ds_read_b128 v[58:61], v180
	ds_read_b128 v[50:53], v180 offset:1152
	s_add_i32 s44, s19, 160
	s_and_b32 s44, s44, 0xfff
	s_lshl_b32 s44, s44, 6
	s_add_u32 s44, s62, s44
	s_addc_u32 s45, s63, 0
	global_load_dwordx4 v[154:157], v166, s[44:45]
	s_waitcnt vmcnt(3)
	ds_write_b128 v167, v[158:161]
	ds_read_b128 v[218:221], v168
	ds_read_b128 v[222:225], v168 offset:16
	ds_read_b128 v[226:229], v168 offset:32
	ds_read_b128 v[230:233], v168 offset:48
	v_pk_mul_f32 v[38:39], v[38:39], v[148:149] op_sel:[0,1]
	v_pk_mul_f32 v[40:41], v[40:41], v[148:149] op_sel:[0,1]
	v_pk_mul_f32 v[34:35], v[34:35], v[148:149] op_sel:[0,1]
	v_pk_mul_f32 v[36:37], v[36:37], v[148:149] op_sel:[0,1]
	v_pk_mul_f32 v[38:39], v[38:39], s[30:31] op_sel_hi:[1,0]
	v_pk_mul_f32 v[40:41], v[40:41], s[30:31] op_sel_hi:[1,0]
	v_pk_mul_f32 v[34:35], v[34:35], s[30:31] op_sel_hi:[1,0]
	v_pk_mul_f32 v[36:37], v[36:37], s[30:31] op_sel_hi:[1,0]
	v_cvt_pk_bf16_f32 v38, v38, v39
	v_cvt_pk_bf16_f32 v39, v40, v41
	v_cvt_pk_bf16_f32 v40, v34, v35
	v_cvt_pk_bf16_f32 v41, v36, v37
	v_pk_mul_f32 v[46:47], v[46:47], v[148:149] op_sel:[0,1]
	v_pk_mul_f32 v[48:49], v[48:49], v[148:149] op_sel:[0,1]
	v_pk_mul_f32 v[42:43], v[42:43], v[148:149] op_sel:[0,1]
	v_pk_mul_f32 v[44:45], v[44:45], v[148:149] op_sel:[0,1]
	ds_swizzle_b32 v34, v46 offset:0x401f
	ds_swizzle_b32 v35, v47 offset:0x401f
	ds_swizzle_b32 v36, v48 offset:0x401f
	ds_swizzle_b32 v37, v49 offset:0x401f
	ds_swizzle_b32 v162, v42 offset:0x401f
	ds_swizzle_b32 v163, v43 offset:0x401f
	ds_swizzle_b32 v164, v44 offset:0x401f
	ds_swizzle_b32 v165, v45 offset:0x401f
	s_waitcnt lgkmcnt(8)
	v_xor_b32_e32 v226, v201, v226
	v_xor_b32_e32 v227, v201, v227
	v_xor_b32_e32 v228, v201, v228
	v_xor_b32_e32 v229, v201, v229
	v_xor_b32_e32 v230, v201, v230
	v_xor_b32_e32 v231, v201, v231
	v_xor_b32_e32 v232, v201, v232
	v_xor_b32_e32 v233, v201, v233
	s_waitcnt lgkmcnt(4)
	v_mul_f32_e32 v34, v226, v34
	v_fmac_f32_e32 v34, v46, v218
	v_cndmask_b32_e64 v46, v46, v34, s[38:39]
	v_mul_f32_e32 v35, v227, v35
	v_fmac_f32_e32 v35, v47, v219
	v_cndmask_b32_e64 v47, v47, v35, s[38:39]
	v_mul_f32_e32 v36, v228, v36
	v_fmac_f32_e32 v36, v48, v220
	v_cndmask_b32_e64 v48, v48, v36, s[38:39]
	v_mul_f32_e32 v37, v229, v37
	v_fmac_f32_e32 v37, v49, v221
	v_cndmask_b32_e64 v49, v49, v37, s[38:39]
	s_waitcnt lgkmcnt(0)
	v_mul_f32_e32 v162, v230, v162
	v_fmac_f32_e32 v162, v42, v222
	v_cndmask_b32_e64 v42, v42, v162, s[38:39]
	v_mul_f32_e32 v163, v231, v163
	v_fmac_f32_e32 v163, v43, v223
	v_cndmask_b32_e64 v43, v43, v163, s[38:39]
	v_mul_f32_e32 v164, v232, v164
	v_fmac_f32_e32 v164, v44, v224
	v_cndmask_b32_e64 v44, v44, v164, s[38:39]
	v_mul_f32_e32 v165, v233, v165
	v_fmac_f32_e32 v165, v45, v225
	v_cndmask_b32_e64 v45, v45, v165, s[38:39]
	v_pk_mul_f32 v[46:47], v[46:47], s[30:31] op_sel_hi:[1,0]
	v_pk_mul_f32 v[48:49], v[48:49], s[30:31] op_sel_hi:[1,0]
	v_pk_mul_f32 v[42:43], v[42:43], s[30:31] op_sel_hi:[1,0]
	v_pk_mul_f32 v[44:45], v[44:45], s[30:31] op_sel_hi:[1,0]
	v_cvt_pk_bf16_f32 v46, v46, v47
	v_cvt_pk_bf16_f32 v47, v48, v49
	v_cvt_pk_bf16_f32 v48, v42, v43
	v_cvt_pk_bf16_f32 v49, v44, v45
	s_mul_i32 s44, s66, 128
	s_add_u32 s100, s98, s44
	s_addc_u32 s101, s99, 0
	global_store_dwordx4 v200, v[58:61], s[100:101] nt
	s_add_u32 s100, s100, s67
	s_addc_u32 s101, s101, 0
	global_store_dwordx4 v200, v[50:53], s[100:101] nt
	ds_write_b128 v178, v[46:49]
	ds_write_b128 v178, v[38:41] offset:64
	ds_read_b128 v[42:45], v180
	ds_read_b128 v[34:37], v180 offset:1152
	s_add_i32 s44, s19, 176
	s_and_b32 s44, s44, 0xfff
	s_lshl_b32 s44, s44, 6
	s_add_u32 s44, s62, s44
	s_addc_u32 s45, s63, 0
	global_load_dwordx4 v[158:161], v166, s[44:45]
	s_waitcnt vmcnt(3)
	ds_write_b128 v167, v[154:157]
	ds_read_b128 v[218:221], v168
	ds_read_b128 v[222:225], v168 offset:16
	ds_read_b128 v[226:229], v168 offset:32
	ds_read_b128 v[230:233], v168 offset:48
	v_pk_mul_f32 v[22:23], v[22:23], v[146:147] op_sel_hi:[1,0]
	v_pk_mul_f32 v[24:25], v[24:25], v[146:147] op_sel_hi:[1,0]
	v_pk_mul_f32 v[18:19], v[18:19], v[146:147] op_sel_hi:[1,0]
	v_pk_mul_f32 v[20:21], v[20:21], v[146:147] op_sel_hi:[1,0]
	v_pk_mul_f32 v[22:23], v[22:23], s[30:31] op_sel_hi:[1,0]
	v_pk_mul_f32 v[24:25], v[24:25], s[30:31] op_sel_hi:[1,0]
	v_pk_mul_f32 v[18:19], v[18:19], s[30:31] op_sel_hi:[1,0]
	v_pk_mul_f32 v[20:21], v[20:21], s[30:31] op_sel_hi:[1,0]
	v_cvt_pk_bf16_f32 v22, v22, v23
	v_cvt_pk_bf16_f32 v23, v24, v25
	v_cvt_pk_bf16_f32 v24, v18, v19
	v_cvt_pk_bf16_f32 v25, v20, v21
	v_pk_mul_f32 v[30:31], v[30:31], v[146:147] op_sel_hi:[1,0]
	v_pk_mul_f32 v[32:33], v[32:33], v[146:147] op_sel_hi:[1,0]
	v_pk_mul_f32 v[26:27], v[26:27], v[146:147] op_sel_hi:[1,0]
	v_pk_mul_f32 v[28:29], v[28:29], v[146:147] op_sel_hi:[1,0]
	ds_swizzle_b32 v18, v30 offset:0x401f
	ds_swizzle_b32 v19, v31 offset:0x401f
	ds_swizzle_b32 v20, v32 offset:0x401f
	ds_swizzle_b32 v21, v33 offset:0x401f
	ds_swizzle_b32 v162, v26 offset:0x401f
	ds_swizzle_b32 v163, v27 offset:0x401f
	ds_swizzle_b32 v164, v28 offset:0x401f
	ds_swizzle_b32 v165, v29 offset:0x401f
	s_waitcnt lgkmcnt(8)
;     __device__ __forceinline__ void operator()(const f32x4 (&acc)[2][2][4][2], const Unit& u, int wr, int wc, int fr, int fq, PG8_LAS float* stash, int par, PG8_LAS unsigned char* stg, const Unit& un) const {
;     ...
;                     for (int i = 0; i < 4; ++i) { v[i] = acc[ai][bj][m][0][i] * rs; v[4 + i] = acc[ai][bj][m][1][i] * rs; }
;                     if (kind <= 1 && bj == 0) {
;                         const f32x4 c0 = *(const f32x4*)(cs + pos * 16), c1 = *(const f32x4*)(cs + pos * 16 + 4), s0 = *(const f32x4*)(cs + pos * 16 + 8), s1 = *(const f32x4*)(cs + pos * 16 + 12);
; #pragma unroll
;                         for (int i = 0; i < 8; ++i) {
;                             const float c = i < 4 ? c0[i & 3] : c1[i & 3], s = i < 4 ? s0[i & 3] : s1[i & 3];
;                             const float pr = peer_x16(v[i], fq);
;                             const float r = (fq == 0) ? (v[i] * c - pr * s) : (v[i] * c + pr * s);
;                             v[i] = (fq < 2) ? r : v[i];
;                         }
;                     }
;                     if (kind == 0) {
; #pragma unroll
;                         for (int i = 0; i < 8; ++i) v[i] *= C2Q;
;                     }
;                     { u32x4 w; w.x = cvt_pk_bf16(v[0], v[1]); w.y = cvt_pk_bf16(v[2], v[3]); w.z = cvt_pk_bf16(v[4], v[5]); w.w = cvt_pk_bf16(v[6], v[7]);
;                       *(PG8_LAS u32x4*)(stg + fr * 144 + fq * 16 + bj * 64) = w; }
;                 }
;                 {
;                     int kind;
;                     if (odd) kind = (u.pn < 6) ? 0 : (u.pn == 6 ? 1 : 2);
;                     else     kind = (u.pn < 2) ? 0 : (u.pn == 2 ? (wc < 2 ? 1 : 2) : 3);
; #pragma unroll
;                     for (int i = 0; i < 2; ++i) { const int c = fq * 16 + fr + 64 * i, rr = c >> 3, pc = c & 7;
;                         const u32x4 w = *(const PG8_LAS u32x4*)(stg + rr * 144 + pc * 16);
;                         const int rowc = row - fr + rr, posc = rowc & 4095;
;                         if (kind == 1 || kind == 2) {
;                             bf16_t* dst = (kind == 1) ? kd : vt;
;                             if (odd) *(u32x4*)(dst + (size_t)(b * 4 + wc) * (4096 * 64) + (size_t)((posc & 15) * 256 + (posc >> 4)) * 64 + pc * 8) = w;
;                             else     *(u32x4*)(dst + (size_t)(b * 2 + (wc & 1)) * (4096 * 64) + (size_t)posc * 64 + pc * 8) = w;
	v_xor_b32_e32 v226, v201, v226
	v_xor_b32_e32 v227, v201, v227
	v_xor_b32_e32 v228, v201, v228
	v_xor_b32_e32 v229, v201, v229
	v_xor_b32_e32 v230, v201, v230
	v_xor_b32_e32 v231, v201, v231
	v_xor_b32_e32 v232, v201, v232
	v_xor_b32_e32 v233, v201, v233
	s_waitcnt lgkmcnt(4)
	v_mul_f32_e32 v18, v226, v18
	v_fmac_f32_e32 v18, v30, v218
	v_cndmask_b32_e64 v30, v30, v18, s[38:39]
	v_mul_f32_e32 v19, v227, v19
	v_fmac_f32_e32 v19, v31, v219
	v_cndmask_b32_e64 v31, v31, v19, s[38:39]
	v_mul_f32_e32 v20, v228, v20
	v_fmac_f32_e32 v20, v32, v220
	v_cndmask_b32_e64 v32, v32, v20, s[38:39]
	v_mul_f32_e32 v21, v229, v21
	v_fmac_f32_e32 v21, v33, v221
	v_cndmask_b32_e64 v33, v33, v21, s[38:39]
	s_waitcnt lgkmcnt(0)
	v_mul_f32_e32 v162, v230, v162
	v_fmac_f32_e32 v162, v26, v222
	v_cndmask_b32_e64 v26, v26, v162, s[38:39]
	v_mul_f32_e32 v163, v231, v163
	v_fmac_f32_e32 v163, v27, v223
	v_cndmask_b32_e64 v27, v27, v163, s[38:39]
	v_mul_f32_e32 v164, v232, v164
	v_fmac_f32_e32 v164, v28, v224
	v_cndmask_b32_e64 v28, v28, v164, s[38:39]
	v_mul_f32_e32 v165, v233, v165
	v_fmac_f32_e32 v165, v29, v225
	v_cndmask_b32_e64 v29, v29, v165, s[38:39]
	v_pk_mul_f32 v[30:31], v[30:31], s[30:31] op_sel_hi:[1,0]
	v_pk_mul_f32 v[32:33], v[32:33], s[30:31] op_sel_hi:[1,0]
	v_pk_mul_f32 v[26:27], v[26:27], s[30:31] op_sel_hi:[1,0]
	v_pk_mul_f32 v[28:29], v[28:29], s[30:31] op_sel_hi:[1,0]
	v_cvt_pk_bf16_f32 v30, v30, v31
	v_cvt_pk_bf16_f32 v31, v32, v33
	v_cvt_pk_bf16_f32 v32, v26, v27
	v_cvt_pk_bf16_f32 v33, v28, v29
	s_mul_i32 s44, s66, 144
	s_add_u32 s100, s98, s44
	s_addc_u32 s101, s99, 0
	global_store_dwordx4 v200, v[42:45], s[100:101] nt
	s_add_u32 s100, s100, s67
	s_addc_u32 s101, s101, 0
	global_store_dwordx4 v200, v[34:37], s[100:101] nt
	ds_write_b128 v178, v[30:33]
	ds_write_b128 v178, v[22:25] offset:64
	ds_read_b128 v[26:29], v180
	ds_read_b128 v[18:21], v180 offset:1152
	s_waitcnt vmcnt(2)
	ds_write_b128 v167, v[158:161]
	ds_read_b128 v[218:221], v168
	ds_read_b128 v[222:225], v168 offset:16
	ds_read_b128 v[226:229], v168 offset:32
	ds_read_b128 v[230:233], v168 offset:48
	v_pk_mul_f32 v[6:7], v[6:7], v[146:147] op_sel:[0,1]
	v_pk_mul_f32 v[8:9], v[8:9], v[146:147] op_sel:[0,1]
	v_pk_mul_f32 v[2:3], v[2:3], v[146:147] op_sel:[0,1]
	v_pk_mul_f32 v[4:5], v[4:5], v[146:147] op_sel:[0,1]
	v_pk_mul_f32 v[6:7], v[6:7], s[30:31] op_sel_hi:[1,0]
	v_pk_mul_f32 v[8:9], v[8:9], s[30:31] op_sel_hi:[1,0]
	v_pk_mul_f32 v[2:3], v[2:3], s[30:31] op_sel_hi:[1,0]
	v_pk_mul_f32 v[4:5], v[4:5], s[30:31] op_sel_hi:[1,0]
	v_cvt_pk_bf16_f32 v6, v6, v7
	v_cvt_pk_bf16_f32 v7, v8, v9
	v_cvt_pk_bf16_f32 v8, v2, v3
	v_cvt_pk_bf16_f32 v9, v4, v5
	v_pk_mul_f32 v[14:15], v[14:15], v[146:147] op_sel:[0,1]
	v_pk_mul_f32 v[16:17], v[16:17], v[146:147] op_sel:[0,1]
	v_pk_mul_f32 v[10:11], v[10:11], v[146:147] op_sel:[0,1]
	v_pk_mul_f32 v[12:13], v[12:13], v[146:147] op_sel:[0,1]
	ds_swizzle_b32 v2, v14 offset:0x401f
	ds_swizzle_b32 v3, v15 offset:0x401f
	ds_swizzle_b32 v4, v16 offset:0x401f
	ds_swizzle_b32 v5, v17 offset:0x401f
	ds_swizzle_b32 v162, v10 offset:0x401f
	ds_swizzle_b32 v163, v11 offset:0x401f
	ds_swizzle_b32 v164, v12 offset:0x401f
	ds_swizzle_b32 v165, v13 offset:0x401f
	s_waitcnt lgkmcnt(8)
	v_xor_b32_e32 v226, v201, v226
	v_xor_b32_e32 v227, v201, v227
	v_xor_b32_e32 v228, v201, v228
	v_xor_b32_e32 v229, v201, v229
	v_xor_b32_e32 v230, v201, v230
	v_xor_b32_e32 v231, v201, v231
	v_xor_b32_e32 v232, v201, v232
	v_xor_b32_e32 v233, v201, v233
	s_waitcnt lgkmcnt(4)
	v_mul_f32_e32 v2, v226, v2
	v_fmac_f32_e32 v2, v14, v218
	v_cndmask_b32_e64 v14, v14, v2, s[38:39]
	v_mul_f32_e32 v3, v227, v3
	v_fmac_f32_e32 v3, v15, v219
	v_cndmask_b32_e64 v15, v15, v3, s[38:39]
	v_mul_f32_e32 v4, v228, v4
	v_fmac_f32_e32 v4, v16, v220
	v_cndmask_b32_e64 v16, v16, v4, s[38:39]
	v_mul_f32_e32 v5, v229, v5
	v_fmac_f32_e32 v5, v17, v221
	v_cndmask_b32_e64 v17, v17, v5, s[38:39]
	s_waitcnt lgkmcnt(0)
	v_mul_f32_e32 v162, v230, v162
	v_fmac_f32_e32 v162, v10, v222
	v_cndmask_b32_e64 v10, v10, v162, s[38:39]
	v_mul_f32_e32 v163, v231, v163
	v_fmac_f32_e32 v163, v11, v223
	v_cndmask_b32_e64 v11, v11, v163, s[38:39]
	v_mul_f32_e32 v164, v232, v164
	v_fmac_f32_e32 v164, v12, v224
	v_cndmask_b32_e64 v12, v12, v164, s[38:39]
	v_mul_f32_e32 v165, v233, v165
	v_fmac_f32_e32 v165, v13, v225
	v_cndmask_b32_e64 v13, v13, v165, s[38:39]
	v_pk_mul_f32 v[14:15], v[14:15], s[30:31] op_sel_hi:[1,0]
	v_pk_mul_f32 v[16:17], v[16:17], s[30:31] op_sel_hi:[1,0]
	v_pk_mul_f32 v[10:11], v[10:11], s[30:31] op_sel_hi:[1,0]
	v_pk_mul_f32 v[12:13], v[12:13], s[30:31] op_sel_hi:[1,0]
	v_cvt_pk_bf16_f32 v14, v14, v15
	v_cvt_pk_bf16_f32 v15, v16, v17
	v_cvt_pk_bf16_f32 v16, v10, v11
	v_cvt_pk_bf16_f32 v17, v12, v13
	s_mul_i32 s44, s66, 160
	s_add_u32 s100, s98, s44
	s_addc_u32 s101, s99, 0
	global_store_dwordx4 v200, v[26:29], s[100:101] nt
	s_add_u32 s100, s100, s67
	s_addc_u32 s101, s101, 0
	global_store_dwordx4 v200, v[18:21], s[100:101] nt
	ds_write_b128 v178, v[14:17]
	ds_write_b128 v178, v[6:9] offset:64
	ds_read_b128 v[10:13], v180
	ds_read_b128 v[2:5], v180 offset:1152
	s_waitcnt lgkmcnt(0)
	s_mul_i32 s44, s66, 176
	s_add_u32 s100, s98, s44
	s_addc_u32 s101, s99, 0
	global_store_dwordx4 v200, v[10:13], s[100:101] nt
	s_add_u32 s100, s100, s67
	s_addc_u32 s101, s101, 0
	global_store_dwordx4 v200, v[2:5], s[100:101] nt
	s_branch .Lipe_done
;     __device__ __forceinline__ void operator()(const f32x4 (&acc)[2][2][4][2], const Unit& u, int wr, int wc, int fr, int fq, PG8_LAS float* stash, int par, PG8_LAS unsigned char* stg, const Unit& un) const {
;     ...
;                     for (int i = 0; i < 4; ++i) { v[i] = acc[ai][bj][m][0][i] * rs; v[4 + i] = acc[ai][bj][m][1][i] * rs; }
;                     if (kind <= 1 && bj == 0) {
;                         const f32x4 c0 = *(const f32x4*)(cs + pos * 16), c1 = *(const f32x4*)(cs + pos * 16 + 4), s0 = *(const f32x4*)(cs + pos * 16 + 8), s1 = *(const f32x4*)(cs + pos * 16 + 12);
; #pragma unroll
;                         for (int i = 0; i < 8; ++i) {
;                             const float c = i < 4 ? c0[i & 3] : c1[i & 3], s = i < 4 ? s0[i & 3] : s1[i & 3];
;                             const float pr = peer_x16(v[i], fq);
;                             const float r = (fq == 0) ? (v[i] * c - pr * s) : (v[i] * c + pr * s);
;                             v[i] = (fq < 2) ? r : v[i];
;                         }
;                     }
;                     if (kind == 0) {
; #pragma unroll
;                         for (int i = 0; i < 8; ++i) v[i] *= C2Q;
;                     }
;                     { u32x4 w; w.x = cvt_pk_bf16(v[0], v[1]); w.y = cvt_pk_bf16(v[2], v[3]); w.z = cvt_pk_bf16(v[4], v[5]); w.w = cvt_pk_bf16(v[6], v[7]);
;                       *(PG8_LAS u32x4*)(stg + fr * 144 + fq * 16 + bj * 64) = w; }
;                 }
;                 {
;                     int kind;
;                     if (odd) kind = (u.pn < 6) ? 0 : (u.pn == 6 ? 1 : 2);
;                     else     kind = (u.pn < 2) ? 0 : (u.pn == 2 ? (wc < 2 ? 1 : 2) : 3);
; #pragma unroll
;                     for (int i = 0; i < 2; ++i) { const int c = fq * 16 + fr + 64 * i, rr = c >> 3, pc = c & 7;
;                         const u32x4 w = *(const PG8_LAS u32x4*)(stg + rr * 144 + pc * 16);
;                         const int rowc = row - fr + rr, posc = rowc & 4095;
;                         if (kind == 1 || kind == 2) {
;                             bf16_t* dst = (kind == 1) ? kd : vt;
;                             if (odd) *(u32x4*)(dst + (size_t)(b * 4 + wc) * (4096 * 64) + (size_t)((posc & 15) * 256 + (posc >> 4)) * 64 + pc * 8) = w;
;                             else     *(u32x4*)(dst + (size_t)(b * 2 + (wc & 1)) * (4096 * 64) + (size_t)posc * 64 + pc * 8) = w;
.Lipe_K:
	v_mbcnt_lo_u32_b32 v166, -1, 0
	v_mbcnt_hi_u32_b32 v166, -1, v166
	v_readfirstlane_b32 s65, v180
	v_lshrrev_b32_e32 v167, 2, v166
	v_mul_u32_u24_e32 v167, 0x50, v167
	v_and_b32_e32 v168, 3, v166
	v_lshl_add_u32 v167, v168, 4, v167
	v_add_u32_e32 v167, s65, v167
	v_mul_u32_u24_e32 v168, 0x50, v141
	v_add_u32_e32 v168, s65, v168
	v_lshlrev_b32_e32 v166, 4, v166
	s_add_i32 s44, s19, 0
	s_and_b32 s44, s44, 0xfff
	s_lshl_b32 s44, s44, 6
	s_add_u32 s44, s62, s44
	s_addc_u32 s45, s63, 0
	global_load_dwordx4 v[154:157], v166, s[44:45]
	s_add_i32 s44, s19, 16
	s_and_b32 s44, s44, 0xfff
	s_lshl_b32 s44, s44, 6
	s_add_u32 s44, s62, s44
	s_addc_u32 s45, s63, 0
	global_load_dwordx4 v[158:161], v166, s[44:45]
	s_waitcnt vmcnt(1)
	ds_write_b128 v167, v[154:157]
	ds_read_b128 v[218:221], v168
	ds_read_b128 v[222:225], v168 offset:16
	ds_read_b128 v[226:229], v168 offset:32
	ds_read_b128 v[230:233], v168 offset:48
	v_pk_mul_f32 v[118:119], v[118:119], v[152:153] op_sel_hi:[1,0]
	v_pk_mul_f32 v[120:121], v[120:121], v[152:153] op_sel_hi:[1,0]
	v_pk_mul_f32 v[114:115], v[114:115], v[152:153] op_sel_hi:[1,0]
	v_pk_mul_f32 v[116:117], v[116:117], v[152:153] op_sel_hi:[1,0]
	v_cvt_pk_bf16_f32 v118, v118, v119
	v_cvt_pk_bf16_f32 v119, v120, v121
	v_cvt_pk_bf16_f32 v120, v114, v115
	v_cvt_pk_bf16_f32 v121, v116, v117
	v_pk_mul_f32 v[126:127], v[126:127], v[152:153] op_sel_hi:[1,0]
	v_pk_mul_f32 v[128:129], v[128:129], v[152:153] op_sel_hi:[1,0]
	v_pk_mul_f32 v[122:123], v[122:123], v[152:153] op_sel_hi:[1,0]
	v_pk_mul_f32 v[124:125], v[124:125], v[152:153] op_sel_hi:[1,0]
	ds_swizzle_b32 v114, v126 offset:0x401f
	ds_swizzle_b32 v115, v127 offset:0x401f
	ds_swizzle_b32 v116, v128 offset:0x401f
	ds_swizzle_b32 v117, v129 offset:0x401f
	ds_swizzle_b32 v162, v122 offset:0x401f
	ds_swizzle_b32 v163, v123 offset:0x401f
	ds_swizzle_b32 v164, v124 offset:0x401f
	ds_swizzle_b32 v165, v125 offset:0x401f
	s_waitcnt lgkmcnt(8)
	v_xor_b32_e32 v226, v201, v226
	v_xor_b32_e32 v227, v201, v227
	v_xor_b32_e32 v228, v201, v228
	v_xor_b32_e32 v229, v201, v229
	v_xor_b32_e32 v230, v201, v230
	v_xor_b32_e32 v231, v201, v231
	v_xor_b32_e32 v232, v201, v232
	v_xor_b32_e32 v233, v201, v233
	s_waitcnt lgkmcnt(4)
	v_mul_f32_e32 v114, v226, v114
	v_fmac_f32_e32 v114, v126, v218
	v_cndmask_b32_e64 v126, v126, v114, s[38:39]
	v_mul_f32_e32 v115, v227, v115
	v_fmac_f32_e32 v115, v127, v219
	v_cndmask_b32_e64 v127, v127, v115, s[38:39]
	v_mul_f32_e32 v116, v228, v116
	v_fmac_f32_e32 v116, v128, v220
	v_cndmask_b32_e64 v128, v128, v116, s[38:39]
	v_mul_f32_e32 v117, v229, v117
	v_fmac_f32_e32 v117, v129, v221
	v_cndmask_b32_e64 v129, v129, v117, s[38:39]
	s_waitcnt lgkmcnt(0)
	v_mul_f32_e32 v162, v230, v162
	v_fmac_f32_e32 v162, v122, v222
	v_cndmask_b32_e64 v122, v122, v162, s[38:39]
	v_mul_f32_e32 v163, v231, v163
	v_fmac_f32_e32 v163, v123, v223
	v_cndmask_b32_e64 v123, v123, v163, s[38:39]
	v_mul_f32_e32 v164, v232, v164
	v_fmac_f32_e32 v164, v124, v224
	v_cndmask_b32_e64 v124, v124, v164, s[38:39]
	v_mul_f32_e32 v165, v233, v165
	v_fmac_f32_e32 v165, v125, v225
	v_cndmask_b32_e64 v125, v125, v165, s[38:39]
	v_cvt_pk_bf16_f32 v126, v126, v127
	v_cvt_pk_bf16_f32 v127, v128, v129
	v_cvt_pk_bf16_f32 v128, v122, v123
	v_cvt_pk_bf16_f32 v129, v124, v125
	ds_write_b128 v178, v[126:129]
	ds_write_b128 v178, v[118:121] offset:64
	ds_read_b128 v[122:125], v180
	ds_read_b128 v[114:117], v180 offset:1152
	s_add_i32 s44, s19, 32
	s_and_b32 s44, s44, 0xfff
	s_lshl_b32 s44, s44, 6
	s_add_u32 s44, s62, s44
	s_addc_u32 s45, s63, 0
	global_load_dwordx4 v[154:157], v166, s[44:45]
	s_waitcnt vmcnt(1)
	ds_write_b128 v167, v[158:161]
	ds_read_b128 v[218:221], v168
	ds_read_b128 v[222:225], v168 offset:16
	ds_read_b128 v[226:229], v168 offset:32
	ds_read_b128 v[230:233], v168 offset:48
	v_pk_mul_f32 v[102:103], v[102:103], v[152:153] op_sel:[0,1]
	v_pk_mul_f32 v[104:105], v[104:105], v[152:153] op_sel:[0,1]
	v_pk_mul_f32 v[98:99], v[98:99], v[152:153] op_sel:[0,1]
	v_pk_mul_f32 v[100:101], v[100:101], v[152:153] op_sel:[0,1]
	v_cvt_pk_bf16_f32 v102, v102, v103
	v_cvt_pk_bf16_f32 v103, v104, v105
	v_cvt_pk_bf16_f32 v104, v98, v99
	v_cvt_pk_bf16_f32 v105, v100, v101
	v_pk_mul_f32 v[110:111], v[110:111], v[152:153] op_sel:[0,1]
	v_pk_mul_f32 v[112:113], v[112:113], v[152:153] op_sel:[0,1]
	v_pk_mul_f32 v[106:107], v[106:107], v[152:153] op_sel:[0,1]
	v_pk_mul_f32 v[108:109], v[108:109], v[152:153] op_sel:[0,1]
	ds_swizzle_b32 v98, v110 offset:0x401f
	ds_swizzle_b32 v99, v111 offset:0x401f
	ds_swizzle_b32 v100, v112 offset:0x401f
	ds_swizzle_b32 v101, v113 offset:0x401f
	ds_swizzle_b32 v162, v106 offset:0x401f
	ds_swizzle_b32 v163, v107 offset:0x401f
	ds_swizzle_b32 v164, v108 offset:0x401f
	ds_swizzle_b32 v165, v109 offset:0x401f
	s_waitcnt lgkmcnt(8)
	v_xor_b32_e32 v226, v201, v226
	v_xor_b32_e32 v227, v201, v227
	v_xor_b32_e32 v228, v201, v228
	v_xor_b32_e32 v229, v201, v229
	v_xor_b32_e32 v230, v201, v230
	v_xor_b32_e32 v231, v201, v231
	v_xor_b32_e32 v232, v201, v232
	v_xor_b32_e32 v233, v201, v233
	s_waitcnt lgkmcnt(4)
	v_mul_f32_e32 v98, v226, v98
	v_fmac_f32_e32 v98, v110, v218
	v_cndmask_b32_e64 v110, v110, v98, s[38:39]
	v_mul_f32_e32 v99, v227, v99
	v_fmac_f32_e32 v99, v111, v219
	v_cndmask_b32_e64 v111, v111, v99, s[38:39]
	v_mul_f32_e32 v100, v228, v100
	v_fmac_f32_e32 v100, v112, v220
	v_cndmask_b32_e64 v112, v112, v100, s[38:39]
	v_mul_f32_e32 v101, v229, v101
	v_fmac_f32_e32 v101, v113, v221
	v_cndmask_b32_e64 v113, v113, v101, s[38:39]
	s_waitcnt lgkmcnt(0)
;     __device__ __forceinline__ void operator()(const f32x4 (&acc)[2][2][4][2], const Unit& u, int wr, int wc, int fr, int fq, PG8_LAS float* stash, int par, PG8_LAS unsigned char* stg, const Unit& un) const {
;     ...
;                     for (int i = 0; i < 4; ++i) { v[i] = acc[ai][bj][m][0][i] * rs; v[4 + i] = acc[ai][bj][m][1][i] * rs; }
;                     if (kind <= 1 && bj == 0) {
;                         const f32x4 c0 = *(const f32x4*)(cs + pos * 16), c1 = *(const f32x4*)(cs + pos * 16 + 4), s0 = *(const f32x4*)(cs + pos * 16 + 8), s1 = *(const f32x4*)(cs + pos * 16 + 12);
; #pragma unroll
;                         for (int i = 0; i < 8; ++i) {
;                             const float c = i < 4 ? c0[i & 3] : c1[i & 3], s = i < 4 ? s0[i & 3] : s1[i & 3];
;                             const float pr = peer_x16(v[i], fq);
;                             const float r = (fq == 0) ? (v[i] * c - pr * s) : (v[i] * c + pr * s);
;                             v[i] = (fq < 2) ? r : v[i];
;                         }
;                     }
;                     if (kind == 0) {
; #pragma unroll
;                         for (int i = 0; i < 8; ++i) v[i] *= C2Q;
;                     }
;                     { u32x4 w; w.x = cvt_pk_bf16(v[0], v[1]); w.y = cvt_pk_bf16(v[2], v[3]); w.z = cvt_pk_bf16(v[4], v[5]); w.w = cvt_pk_bf16(v[6], v[7]);
;                       *(PG8_LAS u32x4*)(stg + fr * 144 + fq * 16 + bj * 64) = w; }
;                 }
;                 {
;                     int kind;
;                     if (odd) kind = (u.pn < 6) ? 0 : (u.pn == 6 ? 1 : 2);
;                     else     kind = (u.pn < 2) ? 0 : (u.pn == 2 ? (wc < 2 ? 1 : 2) : 3);
; #pragma unroll
;                     for (int i = 0; i < 2; ++i) { const int c = fq * 16 + fr + 64 * i, rr = c >> 3, pc = c & 7;
;                         const u32x4 w = *(const PG8_LAS u32x4*)(stg + rr * 144 + pc * 16);
;                         const int rowc = row - fr + rr, posc = rowc & 4095;
;                         if (kind == 1 || kind == 2) {
;                             bf16_t* dst = (kind == 1) ? kd : vt;
;                             if (odd) *(u32x4*)(dst + (size_t)(b * 4 + wc) * (4096 * 64) + (size_t)((posc & 15) * 256 + (posc >> 4)) * 64 + pc * 8) = w;
;                             else     *(u32x4*)(dst + (size_t)(b * 2 + (wc & 1)) * (4096 * 64) + (size_t)posc * 64 + pc * 8) = w;
	v_mul_f32_e32 v162, v230, v162
	v_fmac_f32_e32 v162, v106, v222
	v_cndmask_b32_e64 v106, v106, v162, s[38:39]
	v_mul_f32_e32 v163, v231, v163
	v_fmac_f32_e32 v163, v107, v223
	v_cndmask_b32_e64 v107, v107, v163, s[38:39]
	v_mul_f32_e32 v164, v232, v164
	v_fmac_f32_e32 v164, v108, v224
	v_cndmask_b32_e64 v108, v108, v164, s[38:39]
	v_mul_f32_e32 v165, v233, v165
	v_fmac_f32_e32 v165, v109, v225
	v_cndmask_b32_e64 v109, v109, v165, s[38:39]
	v_cvt_pk_bf16_f32 v110, v110, v111
	v_cvt_pk_bf16_f32 v111, v112, v113
	v_cvt_pk_bf16_f32 v112, v106, v107
	v_cvt_pk_bf16_f32 v113, v108, v109
	s_mov_b32 s100, s98
	s_mov_b32 s101, s99
	global_store_dwordx4 v200, v[122:125], s[100:101] nt
	s_add_u32 s100, s100, s67
	s_addc_u32 s101, s101, 0
	global_store_dwordx4 v200, v[114:117], s[100:101] nt
	ds_write_b128 v178, v[110:113]
	ds_write_b128 v178, v[102:105] offset:64
	ds_read_b128 v[106:109], v180
	ds_read_b128 v[98:101], v180 offset:1152
	s_add_i32 s44, s19, 48
	s_and_b32 s44, s44, 0xfff
	s_lshl_b32 s44, s44, 6
	s_add_u32 s44, s62, s44
	s_addc_u32 s45, s63, 0
	global_load_dwordx4 v[158:161], v166, s[44:45]
	s_waitcnt vmcnt(3)
	ds_write_b128 v167, v[154:157]
	ds_read_b128 v[218:221], v168
	ds_read_b128 v[222:225], v168 offset:16
	ds_read_b128 v[226:229], v168 offset:32
	ds_read_b128 v[230:233], v168 offset:48
	v_pk_mul_f32 v[86:87], v[86:87], v[150:151] op_sel_hi:[1,0]
	v_pk_mul_f32 v[88:89], v[88:89], v[150:151] op_sel_hi:[1,0]
	v_pk_mul_f32 v[82:83], v[82:83], v[150:151] op_sel_hi:[1,0]
	v_pk_mul_f32 v[84:85], v[84:85], v[150:151] op_sel_hi:[1,0]
	v_cvt_pk_bf16_f32 v86, v86, v87
	v_cvt_pk_bf16_f32 v87, v88, v89
	v_cvt_pk_bf16_f32 v88, v82, v83
	v_cvt_pk_bf16_f32 v89, v84, v85
	v_pk_mul_f32 v[94:95], v[94:95], v[150:151] op_sel_hi:[1,0]
	v_pk_mul_f32 v[96:97], v[96:97], v[150:151] op_sel_hi:[1,0]
	v_pk_mul_f32 v[90:91], v[90:91], v[150:151] op_sel_hi:[1,0]
	v_pk_mul_f32 v[92:93], v[92:93], v[150:151] op_sel_hi:[1,0]
	ds_swizzle_b32 v82, v94 offset:0x401f
	ds_swizzle_b32 v83, v95 offset:0x401f
	ds_swizzle_b32 v84, v96 offset:0x401f
	ds_swizzle_b32 v85, v97 offset:0x401f
	ds_swizzle_b32 v162, v90 offset:0x401f
	ds_swizzle_b32 v163, v91 offset:0x401f
	ds_swizzle_b32 v164, v92 offset:0x401f
	ds_swizzle_b32 v165, v93 offset:0x401f
	s_waitcnt lgkmcnt(8)
	v_xor_b32_e32 v226, v201, v226
	v_xor_b32_e32 v227, v201, v227
	v_xor_b32_e32 v228, v201, v228
	v_xor_b32_e32 v229, v201, v229
	v_xor_b32_e32 v230, v201, v230
	v_xor_b32_e32 v231, v201, v231
	v_xor_b32_e32 v232, v201, v232
	v_xor_b32_e32 v233, v201, v233
	s_waitcnt lgkmcnt(4)
	v_mul_f32_e32 v82, v226, v82
	v_fmac_f32_e32 v82, v94, v218
	v_cndmask_b32_e64 v94, v94, v82, s[38:39]
	v_mul_f32_e32 v83, v227, v83
	v_fmac_f32_e32 v83, v95, v219
	v_cndmask_b32_e64 v95, v95, v83, s[38:39]
	v_mul_f32_e32 v84, v228, v84
	v_fmac_f32_e32 v84, v96, v220
	v_cndmask_b32_e64 v96, v96, v84, s[38:39]
	v_mul_f32_e32 v85, v229, v85
	v_fmac_f32_e32 v85, v97, v221
	v_cndmask_b32_e64 v97, v97, v85, s[38:39]
	s_waitcnt lgkmcnt(0)
	v_mul_f32_e32 v162, v230, v162
	v_fmac_f32_e32 v162, v90, v222
	v_cndmask_b32_e64 v90, v90, v162, s[38:39]
	v_mul_f32_e32 v163, v231, v163
	v_fmac_f32_e32 v163, v91, v223
	v_cndmask_b32_e64 v91, v91, v163, s[38:39]
	v_mul_f32_e32 v164, v232, v164
	v_fmac_f32_e32 v164, v92, v224
	v_cndmask_b32_e64 v92, v92, v164, s[38:39]
	v_mul_f32_e32 v165, v233, v165
	v_fmac_f32_e32 v165, v93, v225
	v_cndmask_b32_e64 v93, v93, v165, s[38:39]
	v_cvt_pk_bf16_f32 v94, v94, v95
	v_cvt_pk_bf16_f32 v95, v96, v97
	v_cvt_pk_bf16_f32 v96, v90, v91
	v_cvt_pk_bf16_f32 v97, v92, v93
	s_mul_i32 s44, s66, 16
	s_add_u32 s100, s98, s44
	s_addc_u32 s101, s99, 0
	global_store_dwordx4 v200, v[106:109], s[100:101] nt
	s_add_u32 s100, s100, s67
	s_addc_u32 s101, s101, 0
	global_store_dwordx4 v200, v[98:101], s[100:101] nt
	ds_write_b128 v178, v[94:97]
	ds_write_b128 v178, v[86:89] offset:64
	ds_read_b128 v[90:93], v180
	ds_read_b128 v[82:85], v180 offset:1152
	s_add_i32 s44, s19, 128
	s_and_b32 s44, s44, 0xfff
	s_lshl_b32 s44, s44, 6
	s_add_u32 s44, s62, s44
	s_addc_u32 s45, s63, 0
	global_load_dwordx4 v[154:157], v166, s[44:45]
	s_waitcnt vmcnt(3)
	ds_write_b128 v167, v[158:161]
	ds_read_b128 v[218:221], v168
	ds_read_b128 v[222:225], v168 offset:16
	ds_read_b128 v[226:229], v168 offset:32
	ds_read_b128 v[230:233], v168 offset:48
	v_pk_mul_f32 v[70:71], v[70:71], v[150:151] op_sel:[0,1]
	v_pk_mul_f32 v[72:73], v[72:73], v[150:151] op_sel:[0,1]
	v_pk_mul_f32 v[66:67], v[66:67], v[150:151] op_sel:[0,1]
	v_pk_mul_f32 v[68:69], v[68:69], v[150:151] op_sel:[0,1]
	v_cvt_pk_bf16_f32 v70, v70, v71
	v_cvt_pk_bf16_f32 v71, v72, v73
	v_cvt_pk_bf16_f32 v72, v66, v67
	v_cvt_pk_bf16_f32 v73, v68, v69
	v_pk_mul_f32 v[78:79], v[78:79], v[150:151] op_sel:[0,1]
	v_pk_mul_f32 v[80:81], v[80:81], v[150:151] op_sel:[0,1]
	v_pk_mul_f32 v[74:75], v[74:75], v[150:151] op_sel:[0,1]
	v_pk_mul_f32 v[76:77], v[76:77], v[150:151] op_sel:[0,1]
	ds_swizzle_b32 v66, v78 offset:0x401f
	ds_swizzle_b32 v67, v79 offset:0x401f
	ds_swizzle_b32 v68, v80 offset:0x401f
	ds_swizzle_b32 v69, v81 offset:0x401f
	ds_swizzle_b32 v162, v74 offset:0x401f
	ds_swizzle_b32 v163, v75 offset:0x401f
	ds_swizzle_b32 v164, v76 offset:0x401f
	ds_swizzle_b32 v165, v77 offset:0x401f
	s_waitcnt lgkmcnt(8)
	v_xor_b32_e32 v226, v201, v226
	v_xor_b32_e32 v227, v201, v227
	v_xor_b32_e32 v228, v201, v228
	v_xor_b32_e32 v229, v201, v229
	v_xor_b32_e32 v230, v201, v230
	v_xor_b32_e32 v231, v201, v231
	v_xor_b32_e32 v232, v201, v232
	v_xor_b32_e32 v233, v201, v233
	s_waitcnt lgkmcnt(4)
;     __device__ __forceinline__ void operator()(const f32x4 (&acc)[2][2][4][2], const Unit& u, int wr, int wc, int fr, int fq, PG8_LAS float* stash, int par, PG8_LAS unsigned char* stg, const Unit& un) const {
;     ...
;                     for (int i = 0; i < 4; ++i) { v[i] = acc[ai][bj][m][0][i] * rs; v[4 + i] = acc[ai][bj][m][1][i] * rs; }
;                     if (kind <= 1 && bj == 0) {
;                         const f32x4 c0 = *(const f32x4*)(cs + pos * 16), c1 = *(const f32x4*)(cs + pos * 16 + 4), s0 = *(const f32x4*)(cs + pos * 16 + 8), s1 = *(const f32x4*)(cs + pos * 16 + 12);
; #pragma unroll
;                         for (int i = 0; i < 8; ++i) {
;                             const float c = i < 4 ? c0[i & 3] : c1[i & 3], s = i < 4 ? s0[i & 3] : s1[i & 3];
;                             const float pr = peer_x16(v[i], fq);
;                             const float r = (fq == 0) ? (v[i] * c - pr * s) : (v[i] * c + pr * s);
;                             v[i] = (fq < 2) ? r : v[i];
;                         }
;                     }
;                     if (kind == 0) {
; #pragma unroll
;                         for (int i = 0; i < 8; ++i) v[i] *= C2Q;
;                     }
;                     { u32x4 w; w.x = cvt_pk_bf16(v[0], v[1]); w.y = cvt_pk_bf16(v[2], v[3]); w.z = cvt_pk_bf16(v[4], v[5]); w.w = cvt_pk_bf16(v[6], v[7]);
;                       *(PG8_LAS u32x4*)(stg + fr * 144 + fq * 16 + bj * 64) = w; }
;                 }
;                 {
;                     int kind;
;                     if (odd) kind = (u.pn < 6) ? 0 : (u.pn == 6 ? 1 : 2);
;                     else     kind = (u.pn < 2) ? 0 : (u.pn == 2 ? (wc < 2 ? 1 : 2) : 3);
; #pragma unroll
;                     for (int i = 0; i < 2; ++i) { const int c = fq * 16 + fr + 64 * i, rr = c >> 3, pc = c & 7;
;                         const u32x4 w = *(const PG8_LAS u32x4*)(stg + rr * 144 + pc * 16);
;                         const int rowc = row - fr + rr, posc = rowc & 4095;
;                         if (kind == 1 || kind == 2) {
;                             bf16_t* dst = (kind == 1) ? kd : vt;
;                             if (odd) *(u32x4*)(dst + (size_t)(b * 4 + wc) * (4096 * 64) + (size_t)((posc & 15) * 256 + (posc >> 4)) * 64 + pc * 8) = w;
;                             else     *(u32x4*)(dst + (size_t)(b * 2 + (wc & 1)) * (4096 * 64) + (size_t)posc * 64 + pc * 8) = w;
	v_mul_f32_e32 v66, v226, v66
	v_fmac_f32_e32 v66, v78, v218
	v_cndmask_b32_e64 v78, v78, v66, s[38:39]
	v_mul_f32_e32 v67, v227, v67
	v_fmac_f32_e32 v67, v79, v219
	v_cndmask_b32_e64 v79, v79, v67, s[38:39]
	v_mul_f32_e32 v68, v228, v68
	v_fmac_f32_e32 v68, v80, v220
	v_cndmask_b32_e64 v80, v80, v68, s[38:39]
	v_mul_f32_e32 v69, v229, v69
	v_fmac_f32_e32 v69, v81, v221
	v_cndmask_b32_e64 v81, v81, v69, s[38:39]
	s_waitcnt lgkmcnt(0)
	v_mul_f32_e32 v162, v230, v162
	v_fmac_f32_e32 v162, v74, v222
	v_cndmask_b32_e64 v74, v74, v162, s[38:39]
	v_mul_f32_e32 v163, v231, v163
	v_fmac_f32_e32 v163, v75, v223
	v_cndmask_b32_e64 v75, v75, v163, s[38:39]
	v_mul_f32_e32 v164, v232, v164
	v_fmac_f32_e32 v164, v76, v224
	v_cndmask_b32_e64 v76, v76, v164, s[38:39]
	v_mul_f32_e32 v165, v233, v165
	v_fmac_f32_e32 v165, v77, v225
	v_cndmask_b32_e64 v77, v77, v165, s[38:39]
	v_cvt_pk_bf16_f32 v78, v78, v79
	v_cvt_pk_bf16_f32 v79, v80, v81
	v_cvt_pk_bf16_f32 v80, v74, v75
	v_cvt_pk_bf16_f32 v81, v76, v77
	s_mul_i32 s44, s66, 32
	s_add_u32 s100, s98, s44
	s_addc_u32 s101, s99, 0
	global_store_dwordx4 v200, v[90:93], s[100:101] nt
	s_add_u32 s100, s100, s67
	s_addc_u32 s101, s101, 0
	global_store_dwordx4 v200, v[82:85], s[100:101] nt
	ds_write_b128 v178, v[78:81]
	ds_write_b128 v178, v[70:73] offset:64
	ds_read_b128 v[74:77], v180
	ds_read_b128 v[66:69], v180 offset:1152
	s_add_i32 s44, s19, 144
	s_and_b32 s44, s44, 0xfff
	s_lshl_b32 s44, s44, 6
	s_add_u32 s44, s62, s44
	s_addc_u32 s45, s63, 0
	global_load_dwordx4 v[158:161], v166, s[44:45]
	s_waitcnt vmcnt(3)
	ds_write_b128 v167, v[154:157]
	ds_read_b128 v[218:221], v168
	ds_read_b128 v[222:225], v168 offset:16
	ds_read_b128 v[226:229], v168 offset:32
	ds_read_b128 v[230:233], v168 offset:48
	v_pk_mul_f32 v[54:55], v[54:55], v[148:149] op_sel_hi:[1,0]
	v_pk_mul_f32 v[56:57], v[56:57], v[148:149] op_sel_hi:[1,0]
	v_pk_mul_f32 v[50:51], v[50:51], v[148:149] op_sel_hi:[1,0]
	v_pk_mul_f32 v[52:53], v[52:53], v[148:149] op_sel_hi:[1,0]
	v_cvt_pk_bf16_f32 v54, v54, v55
	v_cvt_pk_bf16_f32 v55, v56, v57
	v_cvt_pk_bf16_f32 v56, v50, v51
	v_cvt_pk_bf16_f32 v57, v52, v53
	v_pk_mul_f32 v[62:63], v[62:63], v[148:149] op_sel_hi:[1,0]
	v_pk_mul_f32 v[64:65], v[64:65], v[148:149] op_sel_hi:[1,0]
	v_pk_mul_f32 v[58:59], v[58:59], v[148:149] op_sel_hi:[1,0]
	v_pk_mul_f32 v[60:61], v[60:61], v[148:149] op_sel_hi:[1,0]
	ds_swizzle_b32 v50, v62 offset:0x401f
	ds_swizzle_b32 v51, v63 offset:0x401f
	ds_swizzle_b32 v52, v64 offset:0x401f
	ds_swizzle_b32 v53, v65 offset:0x401f
	ds_swizzle_b32 v162, v58 offset:0x401f
	ds_swizzle_b32 v163, v59 offset:0x401f
	ds_swizzle_b32 v164, v60 offset:0x401f
	ds_swizzle_b32 v165, v61 offset:0x401f
	s_waitcnt lgkmcnt(8)
	v_xor_b32_e32 v226, v201, v226
	v_xor_b32_e32 v227, v201, v227
	v_xor_b32_e32 v228, v201, v228
	v_xor_b32_e32 v229, v201, v229
	v_xor_b32_e32 v230, v201, v230
	v_xor_b32_e32 v231, v201, v231
	v_xor_b32_e32 v232, v201, v232
	v_xor_b32_e32 v233, v201, v233
	s_waitcnt lgkmcnt(4)
	v_mul_f32_e32 v50, v226, v50
	v_fmac_f32_e32 v50, v62, v218
	v_cndmask_b32_e64 v62, v62, v50, s[38:39]
	v_mul_f32_e32 v51, v227, v51
	v_fmac_f32_e32 v51, v63, v219
	v_cndmask_b32_e64 v63, v63, v51, s[38:39]
	v_mul_f32_e32 v52, v228, v52
	v_fmac_f32_e32 v52, v64, v220
	v_cndmask_b32_e64 v64, v64, v52, s[38:39]
	v_mul_f32_e32 v53, v229, v53
	v_fmac_f32_e32 v53, v65, v221
	v_cndmask_b32_e64 v65, v65, v53, s[38:39]
	s_waitcnt lgkmcnt(0)
	v_mul_f32_e32 v162, v230, v162
	v_fmac_f32_e32 v162, v58, v222
	v_cndmask_b32_e64 v58, v58, v162, s[38:39]
	v_mul_f32_e32 v163, v231, v163
	v_fmac_f32_e32 v163, v59, v223
	v_cndmask_b32_e64 v59, v59, v163, s[38:39]
	v_mul_f32_e32 v164, v232, v164
	v_fmac_f32_e32 v164, v60, v224
	v_cndmask_b32_e64 v60, v60, v164, s[38:39]
	v_mul_f32_e32 v165, v233, v165
	v_fmac_f32_e32 v165, v61, v225
	v_cndmask_b32_e64 v61, v61, v165, s[38:39]
	v_cvt_pk_bf16_f32 v62, v62, v63
	v_cvt_pk_bf16_f32 v63, v64, v65
	v_cvt_pk_bf16_f32 v64, v58, v59
	v_cvt_pk_bf16_f32 v65, v60, v61
	s_mul_i32 s44, s66, 48
	s_add_u32 s100, s98, s44
	s_addc_u32 s101, s99, 0
	global_store_dwordx4 v200, v[74:77], s[100:101] nt
	s_add_u32 s100, s100, s67
	s_addc_u32 s101, s101, 0
	global_store_dwordx4 v200, v[66:69], s[100:101] nt
	ds_write_b128 v178, v[62:65]
	ds_write_b128 v178, v[54:57] offset:64
	ds_read_b128 v[58:61], v180
	ds_read_b128 v[50:53], v180 offset:1152
	s_add_i32 s44, s19, 160
	s_and_b32 s44, s44, 0xfff
	s_lshl_b32 s44, s44, 6
	s_add_u32 s44, s62, s44
	s_addc_u32 s45, s63, 0
	global_load_dwordx4 v[154:157], v166, s[44:45]
	s_waitcnt vmcnt(3)
	ds_write_b128 v167, v[158:161]
	ds_read_b128 v[218:221], v168
	ds_read_b128 v[222:225], v168 offset:16
	ds_read_b128 v[226:229], v168 offset:32
	ds_read_b128 v[230:233], v168 offset:48
	v_pk_mul_f32 v[38:39], v[38:39], v[148:149] op_sel:[0,1]
	v_pk_mul_f32 v[40:41], v[40:41], v[148:149] op_sel:[0,1]
	v_pk_mul_f32 v[34:35], v[34:35], v[148:149] op_sel:[0,1]
	v_pk_mul_f32 v[36:37], v[36:37], v[148:149] op_sel:[0,1]
	v_cvt_pk_bf16_f32 v38, v38, v39
	v_cvt_pk_bf16_f32 v39, v40, v41
	v_cvt_pk_bf16_f32 v40, v34, v35
	v_cvt_pk_bf16_f32 v41, v36, v37
	v_pk_mul_f32 v[46:47], v[46:47], v[148:149] op_sel:[0,1]
	v_pk_mul_f32 v[48:49], v[48:49], v[148:149] op_sel:[0,1]
	v_pk_mul_f32 v[42:43], v[42:43], v[148:149] op_sel:[0,1]
	v_pk_mul_f32 v[44:45], v[44:45], v[148:149] op_sel:[0,1]
	ds_swizzle_b32 v34, v46 offset:0x401f
	ds_swizzle_b32 v35, v47 offset:0x401f
	ds_swizzle_b32 v36, v48 offset:0x401f
	ds_swizzle_b32 v37, v49 offset:0x401f
	ds_swizzle_b32 v162, v42 offset:0x401f
	ds_swizzle_b32 v163, v43 offset:0x401f
	ds_swizzle_b32 v164, v44 offset:0x401f
	ds_swizzle_b32 v165, v45 offset:0x401f
	s_waitcnt lgkmcnt(8)
;     __device__ __forceinline__ void operator()(const f32x4 (&acc)[2][2][4][2], const Unit& u, int wr, int wc, int fr, int fq, PG8_LAS float* stash, int par, PG8_LAS unsigned char* stg, const Unit& un) const {
;     ...
;                     for (int i = 0; i < 4; ++i) { v[i] = acc[ai][bj][m][0][i] * rs; v[4 + i] = acc[ai][bj][m][1][i] * rs; }
;                     if (kind <= 1 && bj == 0) {
;                         const f32x4 c0 = *(const f32x4*)(cs + pos * 16), c1 = *(const f32x4*)(cs + pos * 16 + 4), s0 = *(const f32x4*)(cs + pos * 16 + 8), s1 = *(const f32x4*)(cs + pos * 16 + 12);
; #pragma unroll
;                         for (int i = 0; i < 8; ++i) {
;                             const float c = i < 4 ? c0[i & 3] : c1[i & 3], s = i < 4 ? s0[i & 3] : s1[i & 3];
;                             const float pr = peer_x16(v[i], fq);
;                             const float r = (fq == 0) ? (v[i] * c - pr * s) : (v[i] * c + pr * s);
;                             v[i] = (fq < 2) ? r : v[i];
;                         }
;                     }
;                     if (kind == 0) {
; #pragma unroll
;                         for (int i = 0; i < 8; ++i) v[i] *= C2Q;
;                     }
;                     { u32x4 w; w.x = cvt_pk_bf16(v[0], v[1]); w.y = cvt_pk_bf16(v[2], v[3]); w.z = cvt_pk_bf16(v[4], v[5]); w.w = cvt_pk_bf16(v[6], v[7]);
;                       *(PG8_LAS u32x4*)(stg + fr * 144 + fq * 16 + bj * 64) = w; }
;                 }
;                 {
;                     int kind;
;                     if (odd) kind = (u.pn < 6) ? 0 : (u.pn == 6 ? 1 : 2);
;                     else     kind = (u.pn < 2) ? 0 : (u.pn == 2 ? (wc < 2 ? 1 : 2) : 3);
; #pragma unroll
;                     for (int i = 0; i < 2; ++i) { const int c = fq * 16 + fr + 64 * i, rr = c >> 3, pc = c & 7;
;                         const u32x4 w = *(const PG8_LAS u32x4*)(stg + rr * 144 + pc * 16);
;                         const int rowc = row - fr + rr, posc = rowc & 4095;
;                         if (kind == 1 || kind == 2) {
;                             bf16_t* dst = (kind == 1) ? kd : vt;
;                             if (odd) *(u32x4*)(dst + (size_t)(b * 4 + wc) * (4096 * 64) + (size_t)((posc & 15) * 256 + (posc >> 4)) * 64 + pc * 8) = w;
;                             else     *(u32x4*)(dst + (size_t)(b * 2 + (wc & 1)) * (4096 * 64) + (size_t)posc * 64 + pc * 8) = w;
	v_xor_b32_e32 v226, v201, v226
	v_xor_b32_e32 v227, v201, v227
	v_xor_b32_e32 v228, v201, v228
	v_xor_b32_e32 v229, v201, v229
	v_xor_b32_e32 v230, v201, v230
	v_xor_b32_e32 v231, v201, v231
	v_xor_b32_e32 v232, v201, v232
	v_xor_b32_e32 v233, v201, v233
	s_waitcnt lgkmcnt(4)
	v_mul_f32_e32 v34, v226, v34
	v_fmac_f32_e32 v34, v46, v218
	v_cndmask_b32_e64 v46, v46, v34, s[38:39]
	v_mul_f32_e32 v35, v227, v35
	v_fmac_f32_e32 v35, v47, v219
	v_cndmask_b32_e64 v47, v47, v35, s[38:39]
	v_mul_f32_e32 v36, v228, v36
	v_fmac_f32_e32 v36, v48, v220
	v_cndmask_b32_e64 v48, v48, v36, s[38:39]
	v_mul_f32_e32 v37, v229, v37
	v_fmac_f32_e32 v37, v49, v221
	v_cndmask_b32_e64 v49, v49, v37, s[38:39]
	s_waitcnt lgkmcnt(0)
	v_mul_f32_e32 v162, v230, v162
	v_fmac_f32_e32 v162, v42, v222
	v_cndmask_b32_e64 v42, v42, v162, s[38:39]
	v_mul_f32_e32 v163, v231, v163
	v_fmac_f32_e32 v163, v43, v223
	v_cndmask_b32_e64 v43, v43, v163, s[38:39]
	v_mul_f32_e32 v164, v232, v164
	v_fmac_f32_e32 v164, v44, v224
	v_cndmask_b32_e64 v44, v44, v164, s[38:39]
	v_mul_f32_e32 v165, v233, v165
	v_fmac_f32_e32 v165, v45, v225
	v_cndmask_b32_e64 v45, v45, v165, s[38:39]
	v_cvt_pk_bf16_f32 v46, v46, v47
	v_cvt_pk_bf16_f32 v47, v48, v49
	v_cvt_pk_bf16_f32 v48, v42, v43
	v_cvt_pk_bf16_f32 v49, v44, v45
	s_mul_i32 s44, s66, 128
	s_add_u32 s100, s98, s44
	s_addc_u32 s101, s99, 0
	global_store_dwordx4 v200, v[58:61], s[100:101] nt
	s_add_u32 s100, s100, s67
	s_addc_u32 s101, s101, 0
	global_store_dwordx4 v200, v[50:53], s[100:101] nt
	ds_write_b128 v178, v[46:49]
	ds_write_b128 v178, v[38:41] offset:64
	ds_read_b128 v[42:45], v180
	ds_read_b128 v[34:37], v180 offset:1152
	s_add_i32 s44, s19, 176
	s_and_b32 s44, s44, 0xfff
	s_lshl_b32 s44, s44, 6
	s_add_u32 s44, s62, s44
	s_addc_u32 s45, s63, 0
	global_load_dwordx4 v[158:161], v166, s[44:45]
	s_waitcnt vmcnt(3)
	ds_write_b128 v167, v[154:157]
	ds_read_b128 v[218:221], v168
	ds_read_b128 v[222:225], v168 offset:16
	ds_read_b128 v[226:229], v168 offset:32
	ds_read_b128 v[230:233], v168 offset:48
	v_pk_mul_f32 v[22:23], v[22:23], v[146:147] op_sel_hi:[1,0]
	v_pk_mul_f32 v[24:25], v[24:25], v[146:147] op_sel_hi:[1,0]
	v_pk_mul_f32 v[18:19], v[18:19], v[146:147] op_sel_hi:[1,0]
	v_pk_mul_f32 v[20:21], v[20:21], v[146:147] op_sel_hi:[1,0]
	v_cvt_pk_bf16_f32 v22, v22, v23
	v_cvt_pk_bf16_f32 v23, v24, v25
	v_cvt_pk_bf16_f32 v24, v18, v19
	v_cvt_pk_bf16_f32 v25, v20, v21
	v_pk_mul_f32 v[30:31], v[30:31], v[146:147] op_sel_hi:[1,0]
	v_pk_mul_f32 v[32:33], v[32:33], v[146:147] op_sel_hi:[1,0]
	v_pk_mul_f32 v[26:27], v[26:27], v[146:147] op_sel_hi:[1,0]
	v_pk_mul_f32 v[28:29], v[28:29], v[146:147] op_sel_hi:[1,0]
	ds_swizzle_b32 v18, v30 offset:0x401f
	ds_swizzle_b32 v19, v31 offset:0x401f
	ds_swizzle_b32 v20, v32 offset:0x401f
	ds_swizzle_b32 v21, v33 offset:0x401f
	ds_swizzle_b32 v162, v26 offset:0x401f
	ds_swizzle_b32 v163, v27 offset:0x401f
	ds_swizzle_b32 v164, v28 offset:0x401f
	ds_swizzle_b32 v165, v29 offset:0x401f
	s_waitcnt lgkmcnt(8)
	v_xor_b32_e32 v226, v201, v226
	v_xor_b32_e32 v227, v201, v227
	v_xor_b32_e32 v228, v201, v228
	v_xor_b32_e32 v229, v201, v229
	v_xor_b32_e32 v230, v201, v230
	v_xor_b32_e32 v231, v201, v231
	v_xor_b32_e32 v232, v201, v232
	v_xor_b32_e32 v233, v201, v233
	s_waitcnt lgkmcnt(4)
	v_mul_f32_e32 v18, v226, v18
	v_fmac_f32_e32 v18, v30, v218
	v_cndmask_b32_e64 v30, v30, v18, s[38:39]
	v_mul_f32_e32 v19, v227, v19
	v_fmac_f32_e32 v19, v31, v219
	v_cndmask_b32_e64 v31, v31, v19, s[38:39]
	v_mul_f32_e32 v20, v228, v20
	v_fmac_f32_e32 v20, v32, v220
	v_cndmask_b32_e64 v32, v32, v20, s[38:39]
	v_mul_f32_e32 v21, v229, v21
	v_fmac_f32_e32 v21, v33, v221
	v_cndmask_b32_e64 v33, v33, v21, s[38:39]
	s_waitcnt lgkmcnt(0)
;     __device__ __forceinline__ void operator()(const f32x4 (&acc)[2][2][4][2], const Unit& u, int wr, int wc, int fr, int fq, PG8_LAS float* stash, int par, PG8_LAS unsigned char* stg, const Unit& un) const {
;     ...
;                     for (int i = 0; i < 4; ++i) { v[i] = acc[ai][bj][m][0][i] * rs; v[4 + i] = acc[ai][bj][m][1][i] * rs; }
;                     if (kind <= 1 && bj == 0) {
;                         const f32x4 c0 = *(const f32x4*)(cs + pos * 16), c1 = *(const f32x4*)(cs + pos * 16 + 4), s0 = *(const f32x4*)(cs + pos * 16 + 8), s1 = *(const f32x4*)(cs + pos * 16 + 12);
; #pragma unroll
;                         for (int i = 0; i < 8; ++i) {
;                             const float c = i < 4 ? c0[i & 3] : c1[i & 3], s = i < 4 ? s0[i & 3] : s1[i & 3];
;                             const float pr = peer_x16(v[i], fq);
;                             const float r = (fq == 0) ? (v[i] * c - pr * s) : (v[i] * c + pr * s);
;                             v[i] = (fq < 2) ? r : v[i];
;                         }
;                     }
;                     if (kind == 0) {
; #pragma unroll
;                         for (int i = 0; i < 8; ++i) v[i] *= C2Q;
;                     }
;                     { u32x4 w; w.x = cvt_pk_bf16(v[0], v[1]); w.y = cvt_pk_bf16(v[2], v[3]); w.z = cvt_pk_bf16(v[4], v[5]); w.w = cvt_pk_bf16(v[6], v[7]);
;                       *(PG8_LAS u32x4*)(stg + fr * 144 + fq * 16 + bj * 64) = w; }
;                 }
;                 {
;                     int kind;
;                     if (odd) kind = (u.pn < 6) ? 0 : (u.pn == 6 ? 1 : 2);
;                     else     kind = (u.pn < 2) ? 0 : (u.pn == 2 ? (wc < 2 ? 1 : 2) : 3);
; #pragma unroll
;                     for (int i = 0; i < 2; ++i) { const int c = fq * 16 + fr + 64 * i, rr = c >> 3, pc = c & 7;
;                         const u32x4 w = *(const PG8_LAS u32x4*)(stg + rr * 144 + pc * 16);
;                         const int rowc = row - fr + rr, posc = rowc & 4095;
;                         if (kind == 1 || kind == 2) {
;                             bf16_t* dst = (kind == 1) ? kd : vt;
;                             if (odd) *(u32x4*)(dst + (size_t)(b * 4 + wc) * (4096 * 64) + (size_t)((posc & 15) * 256 + (posc >> 4)) * 64 + pc * 8) = w;
;                             else     *(u32x4*)(dst + (size_t)(b * 2 + (wc & 1)) * (4096 * 64) + (size_t)posc * 64 + pc * 8) = w;
	v_mul_f32_e32 v162, v230, v162
	v_fmac_f32_e32 v162, v26, v222
	v_cndmask_b32_e64 v26, v26, v162, s[38:39]
	v_mul_f32_e32 v163, v231, v163
	v_fmac_f32_e32 v163, v27, v223
	v_cndmask_b32_e64 v27, v27, v163, s[38:39]
	v_mul_f32_e32 v164, v232, v164
	v_fmac_f32_e32 v164, v28, v224
	v_cndmask_b32_e64 v28, v28, v164, s[38:39]
	v_mul_f32_e32 v165, v233, v165
	v_fmac_f32_e32 v165, v29, v225
	v_cndmask_b32_e64 v29, v29, v165, s[38:39]
	v_cvt_pk_bf16_f32 v30, v30, v31
	v_cvt_pk_bf16_f32 v31, v32, v33
	v_cvt_pk_bf16_f32 v32, v26, v27
	v_cvt_pk_bf16_f32 v33, v28, v29
	s_mul_i32 s44, s66, 144
	s_add_u32 s100, s98, s44
	s_addc_u32 s101, s99, 0
	global_store_dwordx4 v200, v[42:45], s[100:101] nt
	s_add_u32 s100, s100, s67
	s_addc_u32 s101, s101, 0
	global_store_dwordx4 v200, v[34:37], s[100:101] nt
	ds_write_b128 v178, v[30:33]
	ds_write_b128 v178, v[22:25] offset:64
	ds_read_b128 v[26:29], v180
	ds_read_b128 v[18:21], v180 offset:1152
	s_waitcnt vmcnt(2)
	ds_write_b128 v167, v[158:161]
	ds_read_b128 v[218:221], v168
	ds_read_b128 v[222:225], v168 offset:16
	ds_read_b128 v[226:229], v168 offset:32
	ds_read_b128 v[230:233], v168 offset:48
	v_pk_mul_f32 v[6:7], v[6:7], v[146:147] op_sel:[0,1]
	v_pk_mul_f32 v[8:9], v[8:9], v[146:147] op_sel:[0,1]
	v_pk_mul_f32 v[2:3], v[2:3], v[146:147] op_sel:[0,1]
	v_pk_mul_f32 v[4:5], v[4:5], v[146:147] op_sel:[0,1]
	v_cvt_pk_bf16_f32 v6, v6, v7
	v_cvt_pk_bf16_f32 v7, v8, v9
	v_cvt_pk_bf16_f32 v8, v2, v3
	v_cvt_pk_bf16_f32 v9, v4, v5
	v_pk_mul_f32 v[14:15], v[14:15], v[146:147] op_sel:[0,1]
	v_pk_mul_f32 v[16:17], v[16:17], v[146:147] op_sel:[0,1]
	v_pk_mul_f32 v[10:11], v[10:11], v[146:147] op_sel:[0,1]
	v_pk_mul_f32 v[12:13], v[12:13], v[146:147] op_sel:[0,1]
	ds_swizzle_b32 v2, v14 offset:0x401f
	ds_swizzle_b32 v3, v15 offset:0x401f
	ds_swizzle_b32 v4, v16 offset:0x401f
	ds_swizzle_b32 v5, v17 offset:0x401f
	ds_swizzle_b32 v162, v10 offset:0x401f
	ds_swizzle_b32 v163, v11 offset:0x401f
	ds_swizzle_b32 v164, v12 offset:0x401f
	ds_swizzle_b32 v165, v13 offset:0x401f
	s_waitcnt lgkmcnt(8)
	v_xor_b32_e32 v226, v201, v226
	v_xor_b32_e32 v227, v201, v227
	v_xor_b32_e32 v228, v201, v228
	v_xor_b32_e32 v229, v201, v229
	v_xor_b32_e32 v230, v201, v230
	v_xor_b32_e32 v231, v201, v231
	v_xor_b32_e32 v232, v201, v232
	v_xor_b32_e32 v233, v201, v233
	s_waitcnt lgkmcnt(4)
	v_mul_f32_e32 v2, v226, v2
	v_fmac_f32_e32 v2, v14, v218
	v_cndmask_b32_e64 v14, v14, v2, s[38:39]
	v_mul_f32_e32 v3, v227, v3
	v_fmac_f32_e32 v3, v15, v219
	v_cndmask_b32_e64 v15, v15, v3, s[38:39]
	v_mul_f32_e32 v4, v228, v4
	v_fmac_f32_e32 v4, v16, v220
	v_cndmask_b32_e64 v16, v16, v4, s[38:39]
	v_mul_f32_e32 v5, v229, v5
	v_fmac_f32_e32 v5, v17, v221
	v_cndmask_b32_e64 v17, v17, v5, s[38:39]
	s_waitcnt lgkmcnt(0)
	v_mul_f32_e32 v162, v230, v162
	v_fmac_f32_e32 v162, v10, v222
	v_cndmask_b32_e64 v10, v10, v162, s[38:39]
	v_mul_f32_e32 v163, v231, v163
	v_fmac_f32_e32 v163, v11, v223
	v_cndmask_b32_e64 v11, v11, v163, s[38:39]
	v_mul_f32_e32 v164, v232, v164
	v_fmac_f32_e32 v164, v12, v224
	v_cndmask_b32_e64 v12, v12, v164, s[38:39]
	v_mul_f32_e32 v165, v233, v165
	v_fmac_f32_e32 v165, v13, v225
	v_cndmask_b32_e64 v13, v13, v165, s[38:39]
	v_cvt_pk_bf16_f32 v14, v14, v15
	v_cvt_pk_bf16_f32 v15, v16, v17
	v_cvt_pk_bf16_f32 v16, v10, v11
	v_cvt_pk_bf16_f32 v17, v12, v13
	s_mul_i32 s44, s66, 160
	s_add_u32 s100, s98, s44
	s_addc_u32 s101, s99, 0
	global_store_dwordx4 v200, v[26:29], s[100:101] nt
	s_add_u32 s100, s100, s67
	s_addc_u32 s101, s101, 0
	global_store_dwordx4 v200, v[18:21], s[100:101] nt
	ds_write_b128 v178, v[14:17]
	ds_write_b128 v178, v[6:9] offset:64
	ds_read_b128 v[10:13], v180
	ds_read_b128 v[2:5], v180 offset:1152
	s_waitcnt lgkmcnt(0)
	s_mul_i32 s44, s66, 176
	s_add_u32 s100, s98, s44
	s_addc_u32 s101, s99, 0
	global_store_dwordx4 v200, v[10:13], s[100:101] nt
	s_add_u32 s100, s100, s67
	s_addc_u32 s101, s101, 0
	global_store_dwordx4 v200, v[2:5], s[100:101] nt
	s_branch .Lipe_done
